# P8 prompt epilogue rewritten: conv taps via DPP-fused v_fmac (no shifted copies/merges), packed silu arithmetic, incremental store addresses (-30% instructions)
# speedup vs baseline: 1.0052x; 1.0052x over previous
.LBB0_1098:
	ds_read_b128 v[130:133], v240
	ds_read_b128 v[134:137], v240 offset:1024
	ds_read_b128 v[138:141], v240 offset:2048
	ds_read_b128 v[142:145], v240 offset:3072
	s_add_u32 s50, s48, 0xfff80080
	s_addc_u32 s51, s49, -1
	s_cmp_eq_u32 s80, s87
	s_cselect_b32 s53, s41, s51
	s_cselect_b32 s52, s47, s50
	s_cselect_b32 s51, s39, s75
	s_cselect_b32 s50, s73, s74
	v_lshl_add_u64 v[168:169], s[48:49], 0, v[166:167]
	s_add_i32 m0, s21, 0xc000
	ds_read_b128 v[146:149], v241
	ds_read_b128 v[150:153], v241 offset:1024
	ds_read_b128 v[154:157], v241 offset:2048
	ds_read_b128 v[158:161], v241 offset:3072
	ds_read_b128 v[176:179], v241 offset:4096
	ds_read_b128 v[180:183], v241 offset:5120
	ds_read_b128 v[184:187], v241 offset:6144
	ds_read_b128 v[188:191], v241 offset:7168
	global_load_lds_dwordx4 v[168:169], off
	v_lshl_add_u64 v[168:169], s[48:49], 0, v[170:171]
	s_add_i32 m0, s21, 0xe000
	s_nop 0
	global_load_lds_dwordx4 v[168:169], off
	s_waitcnt lgkmcnt(8)
	s_barrier
	s_waitcnt lgkmcnt(0)
	s_setprio 1
	s_waitcnt lgkmcnt(0)
	v_mfma_f32_16x16x32_bf16 v[126:129], v[130:133], v[146:149], v[126:129]
	v_mfma_f32_16x16x32_bf16 v[122:125], v[138:141], v[146:149], v[122:125]
	v_mfma_f32_16x16x32_bf16 v[118:121], v[130:133], v[154:157], v[118:121]
	v_mfma_f32_16x16x32_bf16 v[114:117], v[138:141], v[154:157], v[114:117]
	v_mfma_f32_16x16x32_bf16 v[106:109], v[130:133], v[176:179], v[106:109]
	v_mfma_f32_16x16x32_bf16 v[98:101], v[138:141], v[176:179], v[98:101]
	v_mfma_f32_16x16x32_bf16 v[90:93], v[130:133], v[184:187], v[90:93]
	v_mfma_f32_16x16x32_bf16 v[82:85], v[138:141], v[184:187], v[82:85]
	v_mfma_f32_16x16x32_bf16 v[126:129], v[134:137], v[150:153], v[126:129]
	v_mfma_f32_16x16x32_bf16 v[122:125], v[142:145], v[150:153], v[122:125]
	v_mfma_f32_16x16x32_bf16 v[118:121], v[134:137], v[158:161], v[118:121]
	v_mfma_f32_16x16x32_bf16 v[114:117], v[142:145], v[158:161], v[114:117]
	v_mfma_f32_16x16x32_bf16 v[106:109], v[134:137], v[180:183], v[106:109]
	v_mfma_f32_16x16x32_bf16 v[98:101], v[142:145], v[180:183], v[98:101]
	v_mfma_f32_16x16x32_bf16 v[90:93], v[134:137], v[188:191], v[90:93]
	v_mfma_f32_16x16x32_bf16 v[82:85], v[142:145], v[188:191], v[82:85]
	s_setprio 0
	s_barrier
	s_add_i32 s81, s68, s56
	v_lshl_add_u64 v[168:169], s[50:51], 0, v[162:163]
	s_mov_b32 m0, s81
	ds_read_b128 v[192:195], v242
	ds_read_b128 v[196:199], v242 offset:1024
	ds_read_b128 v[200:203], v242 offset:2048
	ds_read_b128 v[204:207], v242 offset:3072
	global_load_lds_dwordx4 v[168:169], off
	v_lshl_add_u64 v[208:209], s[50:51], 0, v[164:165]
	s_add_i32 m0, s81, 0x2000
	s_nop 0
	global_load_lds_dwordx4 v[208:209], off
	s_barrier
	s_waitcnt lgkmcnt(0)
	s_setprio 1
	s_waitcnt lgkmcnt(0)
	v_mfma_f32_16x16x32_bf16 v[110:113], v[192:195], v[146:149], v[110:113]
	v_mfma_f32_16x16x32_bf16 v[102:105], v[200:203], v[146:149], v[102:105]
	v_mfma_f32_16x16x32_bf16 v[94:97], v[192:195], v[154:157], v[94:97]
	v_mfma_f32_16x16x32_bf16 v[86:89], v[200:203], v[154:157], v[86:89]
	v_mfma_f32_16x16x32_bf16 v[78:81], v[192:195], v[176:179], v[78:81]
	v_mfma_f32_16x16x32_bf16 v[74:77], v[200:203], v[176:179], v[74:77]
	v_mfma_f32_16x16x32_bf16 v[70:73], v[192:195], v[184:187], v[70:73]
	v_mfma_f32_16x16x32_bf16 v[66:69], v[200:203], v[184:187], v[66:69]
	v_mfma_f32_16x16x32_bf16 v[110:113], v[196:199], v[150:153], v[110:113]
	v_mfma_f32_16x16x32_bf16 v[102:105], v[204:207], v[150:153], v[102:105]
	v_mfma_f32_16x16x32_bf16 v[94:97], v[196:199], v[158:161], v[94:97]
	v_mfma_f32_16x16x32_bf16 v[86:89], v[204:207], v[158:161], v[86:89]
	v_mfma_f32_16x16x32_bf16 v[78:81], v[196:199], v[180:183], v[78:81]
	v_mfma_f32_16x16x32_bf16 v[74:77], v[204:207], v[180:183], v[74:77]
	v_mfma_f32_16x16x32_bf16 v[70:73], v[196:199], v[188:191], v[70:73]
	v_mfma_f32_16x16x32_bf16 v[66:69], v[204:207], v[188:191], v[66:69]
	s_setprio 0
	s_mov_b32 m0, s21
	v_lshl_add_u64 v[210:211], s[52:53], 0, v[162:163]
	s_barrier
	ds_read_b128 v[146:149], v241 offset:16384
	ds_read_b128 v[150:153], v241 offset:17408
	ds_read_b128 v[154:157], v241 offset:18432
	ds_read_b128 v[158:161], v241 offset:19456
	ds_read_b128 v[176:179], v241 offset:20480
	ds_read_b128 v[180:183], v241 offset:21504
	ds_read_b128 v[184:187], v241 offset:22528
	ds_read_b128 v[188:191], v241 offset:23552
	global_load_lds_dwordx4 v[210:211], off
	v_lshl_add_u64 v[212:213], s[52:53], 0, v[164:165]
	s_mov_b32 m0, s59
	s_nop 0
	global_load_lds_dwordx4 v[212:213], off
	s_barrier
	s_waitcnt lgkmcnt(0)
	s_setprio 1
	s_waitcnt lgkmcnt(0)
	v_mfma_f32_16x16x32_bf16 v[62:65], v[130:133], v[146:149], v[62:65]
	v_mfma_f32_16x16x32_bf16 v[58:61], v[138:141], v[146:149], v[58:61]
	v_mfma_f32_16x16x32_bf16 v[54:57], v[130:133], v[154:157], v[54:57]
	v_mfma_f32_16x16x32_bf16 v[50:53], v[138:141], v[154:157], v[50:53]
	v_mfma_f32_16x16x32_bf16 v[42:45], v[130:133], v[176:179], v[42:45]
	v_mfma_f32_16x16x32_bf16 v[34:37], v[138:141], v[176:179], v[34:37]
	v_mfma_f32_16x16x32_bf16 v[26:29], v[130:133], v[184:187], v[26:29]
	v_mfma_f32_16x16x32_bf16 v[18:21], v[138:141], v[184:187], v[18:21]
	v_mfma_f32_16x16x32_bf16 v[62:65], v[134:137], v[150:153], v[62:65]
	v_mfma_f32_16x16x32_bf16 v[58:61], v[142:145], v[150:153], v[58:61]
	v_mfma_f32_16x16x32_bf16 v[54:57], v[134:137], v[158:161], v[54:57]
	v_mfma_f32_16x16x32_bf16 v[50:53], v[142:145], v[158:161], v[50:53]
	v_mfma_f32_16x16x32_bf16 v[42:45], v[134:137], v[180:183], v[42:45]
	v_mfma_f32_16x16x32_bf16 v[34:37], v[142:145], v[180:183], v[34:37]
	v_mfma_f32_16x16x32_bf16 v[26:29], v[134:137], v[188:191], v[26:29]
	v_mfma_f32_16x16x32_bf16 v[18:21], v[142:145], v[188:191], v[18:21]
	s_setprio 0
	s_barrier
	s_add_u32 s82, s50, 0x80000
	s_addc_u32 s83, s51, 0
	s_add_i32 s81, s69, s56
	v_lshl_add_u64 v[130:131], s[82:83], 0, v[162:163]
	s_mov_b32 m0, s81
	s_nop 0
	global_load_lds_dwordx4 v[130:131], off
	v_lshl_add_u64 v[130:131], s[82:83], 0, v[164:165]
	s_add_i32 m0, s81, 0x2000
	s_nop 0
	global_load_lds_dwordx4 v[130:131], off
	s_waitcnt vmcnt(6)
	s_barrier
	s_setprio 1
	v_mfma_f32_16x16x32_bf16 v[46:49], v[192:195], v[146:149], v[46:49]
	v_mfma_f32_16x16x32_bf16 v[38:41], v[200:203], v[146:149], v[38:41]
	v_mfma_f32_16x16x32_bf16 v[30:33], v[192:195], v[154:157], v[30:33]
	v_mfma_f32_16x16x32_bf16 v[22:25], v[200:203], v[154:157], v[22:25]
	v_mfma_f32_16x16x32_bf16 v[14:17], v[192:195], v[176:179], v[14:17]
	v_mfma_f32_16x16x32_bf16 v[10:13], v[200:203], v[176:179], v[10:13]
	v_mfma_f32_16x16x32_bf16 v[6:9], v[192:195], v[184:187], v[6:9]
	v_mfma_f32_16x16x32_bf16 v[2:5], v[200:203], v[184:187], v[2:5]
	v_mfma_f32_16x16x32_bf16 v[46:49], v[196:199], v[150:153], v[46:49]
	v_mfma_f32_16x16x32_bf16 v[38:41], v[204:207], v[150:153], v[38:41]
	v_mfma_f32_16x16x32_bf16 v[30:33], v[196:199], v[158:161], v[30:33]
	v_mfma_f32_16x16x32_bf16 v[22:25], v[204:207], v[158:161], v[22:25]
	v_mfma_f32_16x16x32_bf16 v[14:17], v[196:199], v[180:183], v[14:17]
	v_mfma_f32_16x16x32_bf16 v[10:13], v[204:207], v[180:183], v[10:13]
	v_mfma_f32_16x16x32_bf16 v[6:9], v[196:199], v[188:191], v[6:9]
	v_mfma_f32_16x16x32_bf16 v[2:5], v[204:207], v[188:191], v[2:5]
	s_setprio 0
	s_add_i32 s81, 0, 0x18000
	v_add_u32_e32 v142, s81, v236
	s_barrier
	ds_read_b128 v[130:133], v142
	ds_read_b128 v[134:137], v142 offset:1024
	ds_read_b128 v[138:141], v142 offset:2048
	ds_read_b128 v[142:145], v142 offset:3072
	s_add_u32 s52, s52, 0x80000
	s_addc_u32 s53, s53, 0
	s_mov_b32 m0, s60
	v_lshl_add_u64 v[192:193], s[52:53], 0, v[162:163]
	ds_read_b128 v[146:149], v241 offset:32768
	ds_read_b128 v[150:153], v241 offset:33792
	ds_read_b128 v[154:157], v241 offset:34816
	ds_read_b128 v[158:161], v241 offset:35840
	ds_read_b128 v[176:179], v241 offset:36864
	ds_read_b128 v[180:183], v241 offset:37888
	ds_read_b128 v[184:187], v241 offset:38912
	ds_read_b128 v[188:191], v241 offset:39936
	global_load_lds_dwordx4 v[192:193], off
	v_lshl_add_u64 v[192:193], s[52:53], 0, v[164:165]
	s_mov_b32 m0, s61
	s_nop 0
	global_load_lds_dwordx4 v[192:193], off
	s_waitcnt lgkmcnt(8)
	s_barrier
	s_waitcnt lgkmcnt(0)
	s_setprio 1
	s_waitcnt lgkmcnt(0)
	v_mfma_f32_16x16x32_bf16 v[126:129], v[130:133], v[146:149], v[126:129]
	v_mfma_f32_16x16x32_bf16 v[122:125], v[138:141], v[146:149], v[122:125]
	v_mfma_f32_16x16x32_bf16 v[118:121], v[130:133], v[154:157], v[118:121]
	v_mfma_f32_16x16x32_bf16 v[114:117], v[138:141], v[154:157], v[114:117]
	v_mfma_f32_16x16x32_bf16 v[106:109], v[130:133], v[176:179], v[106:109]
	v_mfma_f32_16x16x32_bf16 v[98:101], v[138:141], v[176:179], v[98:101]
	v_mfma_f32_16x16x32_bf16 v[90:93], v[130:133], v[184:187], v[90:93]
	v_mfma_f32_16x16x32_bf16 v[82:85], v[138:141], v[184:187], v[82:85]
	v_mfma_f32_16x16x32_bf16 v[126:129], v[134:137], v[150:153], v[126:129]
	v_mfma_f32_16x16x32_bf16 v[122:125], v[142:145], v[150:153], v[122:125]
	v_mfma_f32_16x16x32_bf16 v[118:121], v[134:137], v[158:161], v[118:121]
	v_mfma_f32_16x16x32_bf16 v[114:117], v[142:145], v[158:161], v[114:117]
	v_mfma_f32_16x16x32_bf16 v[106:109], v[134:137], v[180:183], v[106:109]
	v_mfma_f32_16x16x32_bf16 v[98:101], v[142:145], v[180:183], v[98:101]
	v_mfma_f32_16x16x32_bf16 v[90:93], v[134:137], v[188:191], v[90:93]
	v_mfma_f32_16x16x32_bf16 v[82:85], v[142:145], v[188:191], v[82:85]
	s_setprio 0
	s_barrier
	s_add_i32 s52, 0, 0x1c000
	s_add_i32 s53, s81, s56
	v_add_u32_e32 v204, s52, v236
	v_lshl_add_u64 v[168:169], v[168:169], 0, s[36:37]
	s_mov_b32 m0, s53
	ds_read_b128 v[192:195], v204
	ds_read_b128 v[196:199], v204 offset:1024
	ds_read_b128 v[200:203], v204 offset:2048
	ds_read_b128 v[204:207], v204 offset:3072
	global_load_lds_dwordx4 v[168:169], off
	v_lshl_add_u64 v[168:169], v[208:209], 0, s[36:37]
	s_add_i32 m0, s53, 0x2000
	s_nop 0
	global_load_lds_dwordx4 v[168:169], off
	s_barrier
	s_waitcnt lgkmcnt(0)
	s_setprio 1
	s_waitcnt lgkmcnt(0)
	v_mfma_f32_16x16x32_bf16 v[110:113], v[192:195], v[146:149], v[110:113]
	v_mfma_f32_16x16x32_bf16 v[102:105], v[200:203], v[146:149], v[102:105]
	v_mfma_f32_16x16x32_bf16 v[94:97], v[192:195], v[154:157], v[94:97]
	v_mfma_f32_16x16x32_bf16 v[86:89], v[200:203], v[154:157], v[86:89]
	v_mfma_f32_16x16x32_bf16 v[78:81], v[192:195], v[176:179], v[78:81]
	v_mfma_f32_16x16x32_bf16 v[74:77], v[200:203], v[176:179], v[74:77]
	v_mfma_f32_16x16x32_bf16 v[70:73], v[192:195], v[184:187], v[70:73]
	v_mfma_f32_16x16x32_bf16 v[66:69], v[200:203], v[184:187], v[66:69]
	v_mfma_f32_16x16x32_bf16 v[110:113], v[196:199], v[150:153], v[110:113]
	v_mfma_f32_16x16x32_bf16 v[102:105], v[204:207], v[150:153], v[102:105]
	v_mfma_f32_16x16x32_bf16 v[94:97], v[196:199], v[158:161], v[94:97]
	v_mfma_f32_16x16x32_bf16 v[86:89], v[204:207], v[158:161], v[86:89]
	v_mfma_f32_16x16x32_bf16 v[78:81], v[196:199], v[180:183], v[78:81]
	v_mfma_f32_16x16x32_bf16 v[74:77], v[204:207], v[180:183], v[74:77]
	v_mfma_f32_16x16x32_bf16 v[70:73], v[196:199], v[188:191], v[70:73]
	v_mfma_f32_16x16x32_bf16 v[66:69], v[204:207], v[188:191], v[66:69]
	s_setprio 0
	s_mov_b32 m0, s64
	v_lshl_add_u64 v[168:169], v[210:211], 0, s[36:37]
	s_barrier
	ds_read_b128 v[146:149], v241 offset:49152
	ds_read_b128 v[150:153], v241 offset:50176
	ds_read_b128 v[154:157], v241 offset:51200
	ds_read_b128 v[158:161], v241 offset:52224
	ds_read_b128 v[176:179], v241 offset:53248
	ds_read_b128 v[180:183], v241 offset:54272
	ds_read_b128 v[184:187], v241 offset:55296
	ds_read_b128 v[188:191], v241 offset:56320
	global_load_lds_dwordx4 v[168:169], off
	v_lshl_add_u64 v[168:169], v[212:213], 0, s[36:37]
	s_mov_b32 m0, s65
	s_nop 0
	global_load_lds_dwordx4 v[168:169], off
	s_barrier
	s_waitcnt lgkmcnt(0)
	s_setprio 1
	s_waitcnt lgkmcnt(0)
	v_mfma_f32_16x16x32_bf16 v[62:65], v[130:133], v[146:149], v[62:65]
	v_mfma_f32_16x16x32_bf16 v[58:61], v[138:141], v[146:149], v[58:61]
	v_mfma_f32_16x16x32_bf16 v[54:57], v[130:133], v[154:157], v[54:57]
	v_mfma_f32_16x16x32_bf16 v[50:53], v[138:141], v[154:157], v[50:53]
	v_mfma_f32_16x16x32_bf16 v[42:45], v[130:133], v[176:179], v[42:45]
	v_mfma_f32_16x16x32_bf16 v[34:37], v[138:141], v[176:179], v[34:37]
	v_mfma_f32_16x16x32_bf16 v[26:29], v[130:133], v[184:187], v[26:29]
	v_mfma_f32_16x16x32_bf16 v[18:21], v[138:141], v[184:187], v[18:21]
	v_mfma_f32_16x16x32_bf16 v[62:65], v[134:137], v[150:153], v[62:65]
	v_mfma_f32_16x16x32_bf16 v[58:61], v[142:145], v[150:153], v[58:61]
	v_mfma_f32_16x16x32_bf16 v[54:57], v[134:137], v[158:161], v[54:57]
	v_mfma_f32_16x16x32_bf16 v[50:53], v[142:145], v[158:161], v[50:53]
	v_mfma_f32_16x16x32_bf16 v[42:45], v[134:137], v[180:183], v[42:45]
	v_mfma_f32_16x16x32_bf16 v[34:37], v[142:145], v[180:183], v[34:37]
	v_mfma_f32_16x16x32_bf16 v[26:29], v[134:137], v[188:191], v[26:29]
	v_mfma_f32_16x16x32_bf16 v[18:21], v[142:145], v[188:191], v[18:21]
	s_setprio 0
	s_barrier
	s_add_u32 s50, s50, 0x80080
	s_addc_u32 s51, s51, 0
	s_add_i32 s52, s52, s56
	v_lshl_add_u64 v[130:131], s[50:51], 0, v[162:163]
	s_mov_b32 m0, s52
	s_nop 0
	global_load_lds_dwordx4 v[130:131], off
	v_lshl_add_u64 v[130:131], s[50:51], 0, v[164:165]
	s_add_i32 m0, s52, 0x2000
	s_nop 0
	global_load_lds_dwordx4 v[130:131], off
	s_waitcnt vmcnt(6)
	s_barrier
	s_setprio 1
	v_mfma_f32_16x16x32_bf16 v[46:49], v[192:195], v[146:149], v[46:49]
	v_mfma_f32_16x16x32_bf16 v[38:41], v[200:203], v[146:149], v[38:41]
	v_mfma_f32_16x16x32_bf16 v[30:33], v[192:195], v[154:157], v[30:33]
	v_mfma_f32_16x16x32_bf16 v[22:25], v[200:203], v[154:157], v[22:25]
	v_mfma_f32_16x16x32_bf16 v[14:17], v[192:195], v[176:179], v[14:17]
	v_mfma_f32_16x16x32_bf16 v[10:13], v[200:203], v[176:179], v[10:13]
	v_mfma_f32_16x16x32_bf16 v[6:9], v[192:195], v[184:187], v[6:9]
	v_mfma_f32_16x16x32_bf16 v[2:5], v[200:203], v[184:187], v[2:5]
	v_mfma_f32_16x16x32_bf16 v[46:49], v[196:199], v[150:153], v[46:49]
	v_mfma_f32_16x16x32_bf16 v[38:41], v[204:207], v[150:153], v[38:41]
	v_mfma_f32_16x16x32_bf16 v[30:33], v[196:199], v[158:161], v[30:33]
	v_mfma_f32_16x16x32_bf16 v[22:25], v[204:207], v[158:161], v[22:25]
	v_mfma_f32_16x16x32_bf16 v[14:17], v[196:199], v[180:183], v[14:17]
	v_mfma_f32_16x16x32_bf16 v[10:13], v[204:207], v[180:183], v[10:13]
	v_mfma_f32_16x16x32_bf16 v[6:9], v[196:199], v[188:191], v[6:9]
	v_mfma_f32_16x16x32_bf16 v[2:5], v[204:207], v[188:191], v[2:5]
	s_setprio 0
	s_add_i32 s80, s80, 2
	s_add_u32 s48, s48, 0x100
	s_addc_u32 s49, s49, 0
	s_add_u32 s74, s74, 0x100
	s_addc_u32 s75, s75, 0
	s_cmp_gt_u32 s80, s87
	s_barrier
	s_cbranch_scc0 .LBB0_1098
	v_lshl_or_b32 v176, s46, 7, v239
	s_cmp_gt_i32 s20, 63
	v_ashrrev_i32_e32 v177, 31, v176
	s_mov_b64 s[46:47], -1
	s_cbranch_scc1 .LBB0_1141
	v_add_u32_e32 v251, s86, v250
	ds_read_b128 v[130:133], v251
	ds_read_b128 v[146:149], v251 offset:512
	ds_read_b128 v[134:137], v251 offset:1024
	ds_read_b128 v[150:153], v251 offset:1536
	ds_read_b128 v[138:141], v251 offset:2048
	ds_read_b128 v[154:157], v251 offset:2560
	ds_read_b128 v[142:145], v251 offset:3072
	ds_read_b128 v[158:161], v251 offset:3584
	ds_read_b128 v[178:181], v251 offset:64
	ds_read_b128 v[194:197], v251 offset:576
	ds_read_b128 v[182:185], v251 offset:1088
	ds_read_b128 v[198:201], v251 offset:1600
	ds_read_b128 v[186:189], v251 offset:2112
	ds_read_b128 v[202:205], v251 offset:2624
	ds_read_b128 v[190:193], v251 offset:3136
	ds_read_b128 v[206:209], v251 offset:3648
	s_lshl_b32 s39, s20, 2
	s_add_i32 s39, s39, s55
	s_mov_b32 s96, 0x2c000
	s_mov_b32 s97, 0
	s_mov_b32 s48, 0xbfb8aa3b
	v_mov_b32_e32 v211, 0
	v_mov_b32_e32 v213, 0
	v_mov_b32_e32 v215, 0
	v_mov_b32_e32 v217, 0
	v_mov_b32_e32 v219, 0
	v_lshlrev_b32_e32 v243, 2, v176
	v_lshlrev_b32_e32 v244, 1, v176
	v_mul_u32_u24_e32 v210, 0x2c00, v1
	v_add_u32_e32 v210, v210, v244
	v_mul_u32_u24_e32 v212, 0xb000, v1
	v_add_u32_e32 v212, v212, v243
	v_add_u32_e32 v214, 0x5800, v212
	v_mul_i32_i24_e32 v216, 0xb000, v237
	v_add_u32_e32 v216, v216, v243
	v_add_u32_e32 v218, 0x5800, v216
	s_waitcnt lgkmcnt(0)
	s_add_i32 s84, s39, 0
	s_mul_i32 s85, s84, 0xb0000
	s_add_u32 s94, s22, s85
	s_addc_u32 s95, s23, 0
	v_lshl_add_u64 v[220:221], s[94:95], 0, v[210:211]
	s_mul_i32 s85, s84, 0x16000
	s_add_u32 s94, s24, s85
	s_addc_u32 s95, s25, 0
	v_lshl_add_u64 v[222:223], s[94:95], 0, v[212:213]
	v_lshl_add_u64 v[246:247], s[94:95], 0, v[214:215]
	s_and_saveexec_b64 s[46:47], s[4:5]
	global_store_dwordx4 v[222:223], v[126:129], off
	global_store_dwordx4 v[246:247], v[110:113], off
	s_or_b64 exec, exec, s[46:47]
	v_pk_fma_f32 v[224:225], v[126:127], v[138:139], v[142:143]
	v_pk_fma_f32 v[226:227], v[128:129], v[140:141], v[144:145]
	v_pk_fma_f32 v[228:229], v[110:111], v[154:155], v[158:159]
	v_pk_fma_f32 v[230:231], v[112:113], v[156:157], v[160:161]
	v_fmac_f32_dpp v224, v126, v134 row_shr:1 row_mask:0xf bank_mask:0xf bound_ctrl:1
	v_fmac_f32_dpp v225, v127, v135 row_shr:1 row_mask:0xf bank_mask:0xf bound_ctrl:1
	v_fmac_f32_dpp v226, v128, v136 row_shr:1 row_mask:0xf bank_mask:0xf bound_ctrl:1
	v_fmac_f32_dpp v227, v129, v137 row_shr:1 row_mask:0xf bank_mask:0xf bound_ctrl:1
	v_fmac_f32_dpp v228, v110, v150 row_shr:1 row_mask:0xf bank_mask:0xf bound_ctrl:1
	v_fmac_f32_dpp v229, v111, v151 row_shr:1 row_mask:0xf bank_mask:0xf bound_ctrl:1
	v_fmac_f32_dpp v230, v112, v152 row_shr:1 row_mask:0xf bank_mask:0xf bound_ctrl:1
	v_fmac_f32_dpp v231, v113, v153 row_shr:1 row_mask:0xf bank_mask:0xf bound_ctrl:1
	v_fmac_f32_dpp v224, v126, v130 row_shr:2 row_mask:0xf bank_mask:0xf bound_ctrl:1
	v_fmac_f32_dpp v225, v127, v131 row_shr:2 row_mask:0xf bank_mask:0xf bound_ctrl:1
	v_fmac_f32_dpp v226, v128, v132 row_shr:2 row_mask:0xf bank_mask:0xf bound_ctrl:1
	v_fmac_f32_dpp v227, v129, v133 row_shr:2 row_mask:0xf bank_mask:0xf bound_ctrl:1
	v_fmac_f32_dpp v228, v110, v146 row_shr:2 row_mask:0xf bank_mask:0xf bound_ctrl:1
	v_fmac_f32_dpp v229, v111, v147 row_shr:2 row_mask:0xf bank_mask:0xf bound_ctrl:1
	v_fmac_f32_dpp v230, v112, v148 row_shr:2 row_mask:0xf bank_mask:0xf bound_ctrl:1
	v_fmac_f32_dpp v231, v113, v149 row_shr:2 row_mask:0xf bank_mask:0xf bound_ctrl:1
	v_pk_mul_f32 v[232:233], v[224:225], s[48:49] op_sel_hi:[1,0]
	v_pk_mul_f32 v[234:235], v[226:227], s[48:49] op_sel_hi:[1,0]
	v_exp_f32_e32 v232, v232
	v_exp_f32_e32 v233, v233
	v_exp_f32_e32 v234, v234
	v_exp_f32_e32 v235, v235
	s_nop 0
	v_pk_add_f32 v[232:233], v[232:233], 1.0 op_sel_hi:[1,0]
	v_pk_add_f32 v[234:235], v[234:235], 1.0 op_sel_hi:[1,0]
	v_rcp_f32_e32 v232, v232
	v_rcp_f32_e32 v233, v233
	v_rcp_f32_e32 v234, v234
	v_rcp_f32_e32 v235, v235
	s_nop 0
	v_pk_mul_f32 v[224:225], v[224:225], v[232:233]
	v_pk_mul_f32 v[226:227], v[226:227], v[234:235]
	v_pk_mul_f32 v[224:225], v[224:225], v[228:229]
	v_pk_mul_f32 v[226:227], v[226:227], v[230:231]
	s_nop 0
	v_cvt_pk_bf16_f32 v168, v224, v225
	v_cvt_pk_bf16_f32 v169, v226, v227
	s_and_saveexec_b64 s[46:47], s[8:9]
	global_store_dwordx2 v[220:221], v[168:169], off
	s_or_b64 exec, exec, s[46:47]
	v_pk_fma_f32 v[224:225], v[118:119], v[138:139], v[142:143]
	v_pk_fma_f32 v[226:227], v[120:121], v[140:141], v[144:145]
	v_pk_fma_f32 v[228:229], v[94:95], v[154:155], v[158:159]
	v_pk_fma_f32 v[230:231], v[96:97], v[156:157], v[160:161]
	v_fmac_f32_dpp v224, v118, v134 row_shr:1 row_mask:0xf bank_mask:0xf bound_ctrl:1
	v_fmac_f32_dpp v225, v119, v135 row_shr:1 row_mask:0xf bank_mask:0xf bound_ctrl:1
	v_fmac_f32_dpp v226, v120, v136 row_shr:1 row_mask:0xf bank_mask:0xf bound_ctrl:1
	v_fmac_f32_dpp v227, v121, v137 row_shr:1 row_mask:0xf bank_mask:0xf bound_ctrl:1
	v_fmac_f32_dpp v228, v94, v150 row_shr:1 row_mask:0xf bank_mask:0xf bound_ctrl:1
	v_fmac_f32_dpp v229, v95, v151 row_shr:1 row_mask:0xf bank_mask:0xf bound_ctrl:1
	v_fmac_f32_dpp v230, v96, v152 row_shr:1 row_mask:0xf bank_mask:0xf bound_ctrl:1
	v_fmac_f32_dpp v231, v97, v153 row_shr:1 row_mask:0xf bank_mask:0xf bound_ctrl:1
	v_fmac_f32_dpp v224, v118, v130 row_shr:2 row_mask:0xf bank_mask:0xf bound_ctrl:1
	v_fmac_f32_dpp v225, v119, v131 row_shr:2 row_mask:0xf bank_mask:0xf bound_ctrl:1
	v_fmac_f32_dpp v226, v120, v132 row_shr:2 row_mask:0xf bank_mask:0xf bound_ctrl:1
	v_fmac_f32_dpp v227, v121, v133 row_shr:2 row_mask:0xf bank_mask:0xf bound_ctrl:1
	v_fmac_f32_dpp v228, v94, v146 row_shr:2 row_mask:0xf bank_mask:0xf bound_ctrl:1
	v_fmac_f32_dpp v229, v95, v147 row_shr:2 row_mask:0xf bank_mask:0xf bound_ctrl:1
	v_fmac_f32_dpp v230, v96, v148 row_shr:2 row_mask:0xf bank_mask:0xf bound_ctrl:1
	v_fmac_f32_dpp v231, v97, v149 row_shr:2 row_mask:0xf bank_mask:0xf bound_ctrl:1
	v_fmac_f32_dpp v224, v126, v134 row_shl:15 row_mask:0xf bank_mask:0xf bound_ctrl:1
	v_fmac_f32_dpp v225, v127, v135 row_shl:15 row_mask:0xf bank_mask:0xf bound_ctrl:1
	v_fmac_f32_dpp v226, v128, v136 row_shl:15 row_mask:0xf bank_mask:0xf bound_ctrl:1
	v_fmac_f32_dpp v227, v129, v137 row_shl:15 row_mask:0xf bank_mask:0xf bound_ctrl:1
	v_fmac_f32_dpp v228, v110, v150 row_shl:15 row_mask:0xf bank_mask:0xf bound_ctrl:1
	v_fmac_f32_dpp v229, v111, v151 row_shl:15 row_mask:0xf bank_mask:0xf bound_ctrl:1
	v_fmac_f32_dpp v230, v112, v152 row_shl:15 row_mask:0xf bank_mask:0xf bound_ctrl:1
	v_fmac_f32_dpp v231, v113, v153 row_shl:15 row_mask:0xf bank_mask:0xf bound_ctrl:1
	v_fmac_f32_dpp v224, v126, v130 row_shl:14 row_mask:0xf bank_mask:0xf bound_ctrl:1
	v_fmac_f32_dpp v225, v127, v131 row_shl:14 row_mask:0xf bank_mask:0xf bound_ctrl:1
	v_fmac_f32_dpp v226, v128, v132 row_shl:14 row_mask:0xf bank_mask:0xf bound_ctrl:1
	v_fmac_f32_dpp v227, v129, v133 row_shl:14 row_mask:0xf bank_mask:0xf bound_ctrl:1
	v_fmac_f32_dpp v228, v110, v146 row_shl:14 row_mask:0xf bank_mask:0xf bound_ctrl:1
	v_fmac_f32_dpp v229, v111, v147 row_shl:14 row_mask:0xf bank_mask:0xf bound_ctrl:1
	v_fmac_f32_dpp v230, v112, v148 row_shl:14 row_mask:0xf bank_mask:0xf bound_ctrl:1
	v_fmac_f32_dpp v231, v113, v149 row_shl:14 row_mask:0xf bank_mask:0xf bound_ctrl:1
	v_pk_mul_f32 v[232:233], v[224:225], s[48:49] op_sel_hi:[1,0]
	v_pk_mul_f32 v[234:235], v[226:227], s[48:49] op_sel_hi:[1,0]
	v_exp_f32_e32 v232, v232
	v_exp_f32_e32 v233, v233
	v_exp_f32_e32 v234, v234
	v_exp_f32_e32 v235, v235
	s_nop 0
	v_pk_add_f32 v[232:233], v[232:233], 1.0 op_sel_hi:[1,0]
	v_pk_add_f32 v[234:235], v[234:235], 1.0 op_sel_hi:[1,0]
	v_rcp_f32_e32 v232, v232
	v_rcp_f32_e32 v233, v233
	v_rcp_f32_e32 v234, v234
	v_rcp_f32_e32 v235, v235
	v_lshl_add_u64 v[220:221], v[220:221], 0, s[96:97]
	v_pk_mul_f32 v[224:225], v[224:225], v[232:233]
	v_pk_mul_f32 v[226:227], v[226:227], v[234:235]
	v_pk_mul_f32 v[224:225], v[224:225], v[228:229]
	v_pk_mul_f32 v[226:227], v[226:227], v[230:231]
	s_nop 0
	v_cvt_pk_bf16_f32 v168, v224, v225
	v_cvt_pk_bf16_f32 v169, v226, v227
	global_store_dwordx2 v[220:221], v[168:169], off
	v_pk_fma_f32 v[224:225], v[106:107], v[138:139], v[142:143]
	v_pk_fma_f32 v[226:227], v[108:109], v[140:141], v[144:145]
	v_pk_fma_f32 v[228:229], v[78:79], v[154:155], v[158:159]
	v_pk_fma_f32 v[230:231], v[80:81], v[156:157], v[160:161]
	v_fmac_f32_dpp v224, v106, v134 row_shr:1 row_mask:0xf bank_mask:0xf bound_ctrl:1
	v_fmac_f32_dpp v225, v107, v135 row_shr:1 row_mask:0xf bank_mask:0xf bound_ctrl:1
	v_fmac_f32_dpp v226, v108, v136 row_shr:1 row_mask:0xf bank_mask:0xf bound_ctrl:1
	v_fmac_f32_dpp v227, v109, v137 row_shr:1 row_mask:0xf bank_mask:0xf bound_ctrl:1
	v_fmac_f32_dpp v228, v78, v150 row_shr:1 row_mask:0xf bank_mask:0xf bound_ctrl:1
	v_fmac_f32_dpp v229, v79, v151 row_shr:1 row_mask:0xf bank_mask:0xf bound_ctrl:1
	v_fmac_f32_dpp v230, v80, v152 row_shr:1 row_mask:0xf bank_mask:0xf bound_ctrl:1
	v_fmac_f32_dpp v231, v81, v153 row_shr:1 row_mask:0xf bank_mask:0xf bound_ctrl:1
	v_fmac_f32_dpp v224, v106, v130 row_shr:2 row_mask:0xf bank_mask:0xf bound_ctrl:1
	v_fmac_f32_dpp v225, v107, v131 row_shr:2 row_mask:0xf bank_mask:0xf bound_ctrl:1
	v_fmac_f32_dpp v226, v108, v132 row_shr:2 row_mask:0xf bank_mask:0xf bound_ctrl:1
	v_fmac_f32_dpp v227, v109, v133 row_shr:2 row_mask:0xf bank_mask:0xf bound_ctrl:1
	v_fmac_f32_dpp v228, v78, v146 row_shr:2 row_mask:0xf bank_mask:0xf bound_ctrl:1
	v_fmac_f32_dpp v229, v79, v147 row_shr:2 row_mask:0xf bank_mask:0xf bound_ctrl:1
	v_fmac_f32_dpp v230, v80, v148 row_shr:2 row_mask:0xf bank_mask:0xf bound_ctrl:1
	v_fmac_f32_dpp v231, v81, v149 row_shr:2 row_mask:0xf bank_mask:0xf bound_ctrl:1
	v_fmac_f32_dpp v224, v118, v134 row_shl:15 row_mask:0xf bank_mask:0xf bound_ctrl:1
	v_fmac_f32_dpp v225, v119, v135 row_shl:15 row_mask:0xf bank_mask:0xf bound_ctrl:1
	v_fmac_f32_dpp v226, v120, v136 row_shl:15 row_mask:0xf bank_mask:0xf bound_ctrl:1
	v_fmac_f32_dpp v227, v121, v137 row_shl:15 row_mask:0xf bank_mask:0xf bound_ctrl:1
	v_fmac_f32_dpp v228, v94, v150 row_shl:15 row_mask:0xf bank_mask:0xf bound_ctrl:1
	v_fmac_f32_dpp v229, v95, v151 row_shl:15 row_mask:0xf bank_mask:0xf bound_ctrl:1
	v_fmac_f32_dpp v230, v96, v152 row_shl:15 row_mask:0xf bank_mask:0xf bound_ctrl:1
	v_fmac_f32_dpp v231, v97, v153 row_shl:15 row_mask:0xf bank_mask:0xf bound_ctrl:1
	v_fmac_f32_dpp v224, v118, v130 row_shl:14 row_mask:0xf bank_mask:0xf bound_ctrl:1
	v_fmac_f32_dpp v225, v119, v131 row_shl:14 row_mask:0xf bank_mask:0xf bound_ctrl:1
	v_fmac_f32_dpp v226, v120, v132 row_shl:14 row_mask:0xf bank_mask:0xf bound_ctrl:1
	v_fmac_f32_dpp v227, v121, v133 row_shl:14 row_mask:0xf bank_mask:0xf bound_ctrl:1
	v_fmac_f32_dpp v228, v94, v146 row_shl:14 row_mask:0xf bank_mask:0xf bound_ctrl:1
	v_fmac_f32_dpp v229, v95, v147 row_shl:14 row_mask:0xf bank_mask:0xf bound_ctrl:1
	v_fmac_f32_dpp v230, v96, v148 row_shl:14 row_mask:0xf bank_mask:0xf bound_ctrl:1
	v_fmac_f32_dpp v231, v97, v149 row_shl:14 row_mask:0xf bank_mask:0xf bound_ctrl:1
	v_pk_mul_f32 v[232:233], v[224:225], s[48:49] op_sel_hi:[1,0]
	v_pk_mul_f32 v[234:235], v[226:227], s[48:49] op_sel_hi:[1,0]
	v_exp_f32_e32 v232, v232
	v_exp_f32_e32 v233, v233
	v_exp_f32_e32 v234, v234
	v_exp_f32_e32 v235, v235
	s_nop 0
	v_pk_add_f32 v[232:233], v[232:233], 1.0 op_sel_hi:[1,0]
	v_pk_add_f32 v[234:235], v[234:235], 1.0 op_sel_hi:[1,0]
	v_rcp_f32_e32 v232, v232
	v_rcp_f32_e32 v233, v233
	v_rcp_f32_e32 v234, v234
	v_rcp_f32_e32 v235, v235
	v_lshl_add_u64 v[220:221], v[220:221], 0, s[96:97]
	v_pk_mul_f32 v[224:225], v[224:225], v[232:233]
	v_pk_mul_f32 v[226:227], v[226:227], v[234:235]
	v_pk_mul_f32 v[224:225], v[224:225], v[228:229]
	v_pk_mul_f32 v[226:227], v[226:227], v[230:231]
	s_nop 0
	v_cvt_pk_bf16_f32 v168, v224, v225
	v_cvt_pk_bf16_f32 v169, v226, v227
	global_store_dwordx2 v[220:221], v[168:169], off
	s_add_u32 s94, s26, s85
	s_addc_u32 s95, s27, 0
	v_lshl_add_u64 v[222:223], s[94:95], 0, v[216:217]
	v_lshl_add_u64 v[246:247], s[94:95], 0, v[218:219]
	s_and_saveexec_b64 s[46:47], s[6:7]
	global_store_dwordx4 v[222:223], v[90:93], off
	global_store_dwordx4 v[246:247], v[70:73], off
	s_or_b64 exec, exec, s[46:47]
	v_pk_fma_f32 v[224:225], v[90:91], v[138:139], v[142:143]
	v_pk_fma_f32 v[226:227], v[92:93], v[140:141], v[144:145]
	v_pk_fma_f32 v[228:229], v[70:71], v[154:155], v[158:159]
	v_pk_fma_f32 v[230:231], v[72:73], v[156:157], v[160:161]
	v_fmac_f32_dpp v224, v90, v134 row_shr:1 row_mask:0xf bank_mask:0xf bound_ctrl:1
	v_fmac_f32_dpp v225, v91, v135 row_shr:1 row_mask:0xf bank_mask:0xf bound_ctrl:1
	v_fmac_f32_dpp v226, v92, v136 row_shr:1 row_mask:0xf bank_mask:0xf bound_ctrl:1
	v_fmac_f32_dpp v227, v93, v137 row_shr:1 row_mask:0xf bank_mask:0xf bound_ctrl:1
	v_fmac_f32_dpp v228, v70, v150 row_shr:1 row_mask:0xf bank_mask:0xf bound_ctrl:1
	v_fmac_f32_dpp v229, v71, v151 row_shr:1 row_mask:0xf bank_mask:0xf bound_ctrl:1
	v_fmac_f32_dpp v230, v72, v152 row_shr:1 row_mask:0xf bank_mask:0xf bound_ctrl:1
	v_fmac_f32_dpp v231, v73, v153 row_shr:1 row_mask:0xf bank_mask:0xf bound_ctrl:1
	v_fmac_f32_dpp v224, v90, v130 row_shr:2 row_mask:0xf bank_mask:0xf bound_ctrl:1
	v_fmac_f32_dpp v225, v91, v131 row_shr:2 row_mask:0xf bank_mask:0xf bound_ctrl:1
	v_fmac_f32_dpp v226, v92, v132 row_shr:2 row_mask:0xf bank_mask:0xf bound_ctrl:1
	v_fmac_f32_dpp v227, v93, v133 row_shr:2 row_mask:0xf bank_mask:0xf bound_ctrl:1
	v_fmac_f32_dpp v228, v70, v146 row_shr:2 row_mask:0xf bank_mask:0xf bound_ctrl:1
	v_fmac_f32_dpp v229, v71, v147 row_shr:2 row_mask:0xf bank_mask:0xf bound_ctrl:1
	v_fmac_f32_dpp v230, v72, v148 row_shr:2 row_mask:0xf bank_mask:0xf bound_ctrl:1
	v_fmac_f32_dpp v231, v73, v149 row_shr:2 row_mask:0xf bank_mask:0xf bound_ctrl:1
	v_fmac_f32_dpp v224, v106, v134 row_shl:15 row_mask:0xf bank_mask:0xf bound_ctrl:1
	v_fmac_f32_dpp v225, v107, v135 row_shl:15 row_mask:0xf bank_mask:0xf bound_ctrl:1
	v_fmac_f32_dpp v226, v108, v136 row_shl:15 row_mask:0xf bank_mask:0xf bound_ctrl:1
	v_fmac_f32_dpp v227, v109, v137 row_shl:15 row_mask:0xf bank_mask:0xf bound_ctrl:1
	v_fmac_f32_dpp v228, v78, v150 row_shl:15 row_mask:0xf bank_mask:0xf bound_ctrl:1
	v_fmac_f32_dpp v229, v79, v151 row_shl:15 row_mask:0xf bank_mask:0xf bound_ctrl:1
	v_fmac_f32_dpp v230, v80, v152 row_shl:15 row_mask:0xf bank_mask:0xf bound_ctrl:1
	v_fmac_f32_dpp v231, v81, v153 row_shl:15 row_mask:0xf bank_mask:0xf bound_ctrl:1
	v_fmac_f32_dpp v224, v106, v130 row_shl:14 row_mask:0xf bank_mask:0xf bound_ctrl:1
	v_fmac_f32_dpp v225, v107, v131 row_shl:14 row_mask:0xf bank_mask:0xf bound_ctrl:1
	v_fmac_f32_dpp v226, v108, v132 row_shl:14 row_mask:0xf bank_mask:0xf bound_ctrl:1
	v_fmac_f32_dpp v227, v109, v133 row_shl:14 row_mask:0xf bank_mask:0xf bound_ctrl:1
	v_fmac_f32_dpp v228, v78, v146 row_shl:14 row_mask:0xf bank_mask:0xf bound_ctrl:1
	v_fmac_f32_dpp v229, v79, v147 row_shl:14 row_mask:0xf bank_mask:0xf bound_ctrl:1
	v_fmac_f32_dpp v230, v80, v148 row_shl:14 row_mask:0xf bank_mask:0xf bound_ctrl:1
	v_fmac_f32_dpp v231, v81, v149 row_shl:14 row_mask:0xf bank_mask:0xf bound_ctrl:1
	v_pk_mul_f32 v[232:233], v[224:225], s[48:49] op_sel_hi:[1,0]
	v_pk_mul_f32 v[234:235], v[226:227], s[48:49] op_sel_hi:[1,0]
	v_exp_f32_e32 v232, v232
	v_exp_f32_e32 v233, v233
	v_exp_f32_e32 v234, v234
	v_exp_f32_e32 v235, v235
	s_nop 0
	v_pk_add_f32 v[232:233], v[232:233], 1.0 op_sel_hi:[1,0]
	v_pk_add_f32 v[234:235], v[234:235], 1.0 op_sel_hi:[1,0]
	v_rcp_f32_e32 v232, v232
	v_rcp_f32_e32 v233, v233
	v_rcp_f32_e32 v234, v234
	v_rcp_f32_e32 v235, v235
	v_lshl_add_u64 v[220:221], v[220:221], 0, s[96:97]
	v_pk_mul_f32 v[224:225], v[224:225], v[232:233]
	v_pk_mul_f32 v[226:227], v[226:227], v[234:235]
	v_pk_mul_f32 v[224:225], v[224:225], v[228:229]
	v_pk_mul_f32 v[226:227], v[226:227], v[230:231]
	s_nop 0
	v_cvt_pk_bf16_f32 v168, v224, v225
	v_cvt_pk_bf16_f32 v169, v226, v227
	global_store_dwordx2 v[220:221], v[168:169], off
	s_add_i32 s84, s39, 2
	s_mul_i32 s85, s84, 0xb0000
	s_add_u32 s94, s22, s85
	s_addc_u32 s95, s23, 0
	v_lshl_add_u64 v[220:221], s[94:95], 0, v[210:211]
	s_mul_i32 s85, s84, 0x16000
	s_add_u32 s94, s24, s85
	s_addc_u32 s95, s25, 0
	v_lshl_add_u64 v[222:223], s[94:95], 0, v[212:213]
	v_lshl_add_u64 v[246:247], s[94:95], 0, v[214:215]
	s_and_saveexec_b64 s[46:47], s[4:5]
	global_store_dwordx4 v[222:223], v[62:65], off
	global_store_dwordx4 v[246:247], v[46:49], off
	s_or_b64 exec, exec, s[46:47]
	v_pk_fma_f32 v[224:225], v[62:63], v[138:139], v[142:143]
	v_pk_fma_f32 v[226:227], v[64:65], v[140:141], v[144:145]
	v_pk_fma_f32 v[228:229], v[46:47], v[154:155], v[158:159]
	v_pk_fma_f32 v[230:231], v[48:49], v[156:157], v[160:161]
	v_fmac_f32_dpp v224, v62, v134 row_shr:1 row_mask:0xf bank_mask:0xf bound_ctrl:1
	v_fmac_f32_dpp v225, v63, v135 row_shr:1 row_mask:0xf bank_mask:0xf bound_ctrl:1
	v_fmac_f32_dpp v226, v64, v136 row_shr:1 row_mask:0xf bank_mask:0xf bound_ctrl:1
	v_fmac_f32_dpp v227, v65, v137 row_shr:1 row_mask:0xf bank_mask:0xf bound_ctrl:1
	v_fmac_f32_dpp v228, v46, v150 row_shr:1 row_mask:0xf bank_mask:0xf bound_ctrl:1
	v_fmac_f32_dpp v229, v47, v151 row_shr:1 row_mask:0xf bank_mask:0xf bound_ctrl:1
	v_fmac_f32_dpp v230, v48, v152 row_shr:1 row_mask:0xf bank_mask:0xf bound_ctrl:1
	v_fmac_f32_dpp v231, v49, v153 row_shr:1 row_mask:0xf bank_mask:0xf bound_ctrl:1
	v_fmac_f32_dpp v224, v62, v130 row_shr:2 row_mask:0xf bank_mask:0xf bound_ctrl:1
	v_fmac_f32_dpp v225, v63, v131 row_shr:2 row_mask:0xf bank_mask:0xf bound_ctrl:1
	v_fmac_f32_dpp v226, v64, v132 row_shr:2 row_mask:0xf bank_mask:0xf bound_ctrl:1
	v_fmac_f32_dpp v227, v65, v133 row_shr:2 row_mask:0xf bank_mask:0xf bound_ctrl:1
	v_fmac_f32_dpp v228, v46, v146 row_shr:2 row_mask:0xf bank_mask:0xf bound_ctrl:1
	v_fmac_f32_dpp v229, v47, v147 row_shr:2 row_mask:0xf bank_mask:0xf bound_ctrl:1
	v_fmac_f32_dpp v230, v48, v148 row_shr:2 row_mask:0xf bank_mask:0xf bound_ctrl:1
	v_fmac_f32_dpp v231, v49, v149 row_shr:2 row_mask:0xf bank_mask:0xf bound_ctrl:1
	v_pk_mul_f32 v[232:233], v[224:225], s[48:49] op_sel_hi:[1,0]
	v_pk_mul_f32 v[234:235], v[226:227], s[48:49] op_sel_hi:[1,0]
	v_exp_f32_e32 v232, v232
	v_exp_f32_e32 v233, v233
	v_exp_f32_e32 v234, v234
	v_exp_f32_e32 v235, v235
	s_nop 0
	v_pk_add_f32 v[232:233], v[232:233], 1.0 op_sel_hi:[1,0]
	v_pk_add_f32 v[234:235], v[234:235], 1.0 op_sel_hi:[1,0]
	v_rcp_f32_e32 v232, v232
	v_rcp_f32_e32 v233, v233
	v_rcp_f32_e32 v234, v234
	v_rcp_f32_e32 v235, v235
	s_nop 0
	v_pk_mul_f32 v[224:225], v[224:225], v[232:233]
	v_pk_mul_f32 v[226:227], v[226:227], v[234:235]
	v_pk_mul_f32 v[224:225], v[224:225], v[228:229]
	v_pk_mul_f32 v[226:227], v[226:227], v[230:231]
	s_nop 0
	v_cvt_pk_bf16_f32 v168, v224, v225
	v_cvt_pk_bf16_f32 v169, v226, v227
	s_and_saveexec_b64 s[46:47], s[8:9]
	global_store_dwordx2 v[220:221], v[168:169], off
	s_or_b64 exec, exec, s[46:47]
	v_pk_fma_f32 v[224:225], v[54:55], v[138:139], v[142:143]
	v_pk_fma_f32 v[226:227], v[56:57], v[140:141], v[144:145]
	v_pk_fma_f32 v[228:229], v[30:31], v[154:155], v[158:159]
	v_pk_fma_f32 v[230:231], v[32:33], v[156:157], v[160:161]
	v_fmac_f32_dpp v224, v54, v134 row_shr:1 row_mask:0xf bank_mask:0xf bound_ctrl:1
	v_fmac_f32_dpp v225, v55, v135 row_shr:1 row_mask:0xf bank_mask:0xf bound_ctrl:1
	v_fmac_f32_dpp v226, v56, v136 row_shr:1 row_mask:0xf bank_mask:0xf bound_ctrl:1
	v_fmac_f32_dpp v227, v57, v137 row_shr:1 row_mask:0xf bank_mask:0xf bound_ctrl:1
	v_fmac_f32_dpp v228, v30, v150 row_shr:1 row_mask:0xf bank_mask:0xf bound_ctrl:1
	v_fmac_f32_dpp v229, v31, v151 row_shr:1 row_mask:0xf bank_mask:0xf bound_ctrl:1
	v_fmac_f32_dpp v230, v32, v152 row_shr:1 row_mask:0xf bank_mask:0xf bound_ctrl:1
	v_fmac_f32_dpp v231, v33, v153 row_shr:1 row_mask:0xf bank_mask:0xf bound_ctrl:1
	v_fmac_f32_dpp v224, v54, v130 row_shr:2 row_mask:0xf bank_mask:0xf bound_ctrl:1
	v_fmac_f32_dpp v225, v55, v131 row_shr:2 row_mask:0xf bank_mask:0xf bound_ctrl:1
	v_fmac_f32_dpp v226, v56, v132 row_shr:2 row_mask:0xf bank_mask:0xf bound_ctrl:1
	v_fmac_f32_dpp v227, v57, v133 row_shr:2 row_mask:0xf bank_mask:0xf bound_ctrl:1
	v_fmac_f32_dpp v228, v30, v146 row_shr:2 row_mask:0xf bank_mask:0xf bound_ctrl:1
	v_fmac_f32_dpp v229, v31, v147 row_shr:2 row_mask:0xf bank_mask:0xf bound_ctrl:1
	v_fmac_f32_dpp v230, v32, v148 row_shr:2 row_mask:0xf bank_mask:0xf bound_ctrl:1
	v_fmac_f32_dpp v231, v33, v149 row_shr:2 row_mask:0xf bank_mask:0xf bound_ctrl:1
	v_fmac_f32_dpp v224, v62, v134 row_shl:15 row_mask:0xf bank_mask:0xf bound_ctrl:1
	v_fmac_f32_dpp v225, v63, v135 row_shl:15 row_mask:0xf bank_mask:0xf bound_ctrl:1
	v_fmac_f32_dpp v226, v64, v136 row_shl:15 row_mask:0xf bank_mask:0xf bound_ctrl:1
	v_fmac_f32_dpp v227, v65, v137 row_shl:15 row_mask:0xf bank_mask:0xf bound_ctrl:1
	v_fmac_f32_dpp v228, v46, v150 row_shl:15 row_mask:0xf bank_mask:0xf bound_ctrl:1
	v_fmac_f32_dpp v229, v47, v151 row_shl:15 row_mask:0xf bank_mask:0xf bound_ctrl:1
	v_fmac_f32_dpp v230, v48, v152 row_shl:15 row_mask:0xf bank_mask:0xf bound_ctrl:1
	v_fmac_f32_dpp v231, v49, v153 row_shl:15 row_mask:0xf bank_mask:0xf bound_ctrl:1
	v_fmac_f32_dpp v224, v62, v130 row_shl:14 row_mask:0xf bank_mask:0xf bound_ctrl:1
	v_fmac_f32_dpp v225, v63, v131 row_shl:14 row_mask:0xf bank_mask:0xf bound_ctrl:1
	v_fmac_f32_dpp v226, v64, v132 row_shl:14 row_mask:0xf bank_mask:0xf bound_ctrl:1
	v_fmac_f32_dpp v227, v65, v133 row_shl:14 row_mask:0xf bank_mask:0xf bound_ctrl:1
	v_fmac_f32_dpp v228, v46, v146 row_shl:14 row_mask:0xf bank_mask:0xf bound_ctrl:1
	v_fmac_f32_dpp v229, v47, v147 row_shl:14 row_mask:0xf bank_mask:0xf bound_ctrl:1
	v_fmac_f32_dpp v230, v48, v148 row_shl:14 row_mask:0xf bank_mask:0xf bound_ctrl:1
	v_fmac_f32_dpp v231, v49, v149 row_shl:14 row_mask:0xf bank_mask:0xf bound_ctrl:1
	v_pk_mul_f32 v[232:233], v[224:225], s[48:49] op_sel_hi:[1,0]
	v_pk_mul_f32 v[234:235], v[226:227], s[48:49] op_sel_hi:[1,0]
	v_exp_f32_e32 v232, v232
	v_exp_f32_e32 v233, v233
	v_exp_f32_e32 v234, v234
	v_exp_f32_e32 v235, v235
	s_nop 0
	v_pk_add_f32 v[232:233], v[232:233], 1.0 op_sel_hi:[1,0]
	v_pk_add_f32 v[234:235], v[234:235], 1.0 op_sel_hi:[1,0]
	v_rcp_f32_e32 v232, v232
	v_rcp_f32_e32 v233, v233
	v_rcp_f32_e32 v234, v234
	v_rcp_f32_e32 v235, v235
	v_lshl_add_u64 v[220:221], v[220:221], 0, s[96:97]
	v_pk_mul_f32 v[224:225], v[224:225], v[232:233]
	v_pk_mul_f32 v[226:227], v[226:227], v[234:235]
	v_pk_mul_f32 v[224:225], v[224:225], v[228:229]
	v_pk_mul_f32 v[226:227], v[226:227], v[230:231]
	s_nop 0
	v_cvt_pk_bf16_f32 v168, v224, v225
	v_cvt_pk_bf16_f32 v169, v226, v227
	global_store_dwordx2 v[220:221], v[168:169], off
	v_pk_fma_f32 v[224:225], v[42:43], v[138:139], v[142:143]
	v_pk_fma_f32 v[226:227], v[44:45], v[140:141], v[144:145]
	v_pk_fma_f32 v[228:229], v[14:15], v[154:155], v[158:159]
	v_pk_fma_f32 v[230:231], v[16:17], v[156:157], v[160:161]
	v_fmac_f32_dpp v224, v42, v134 row_shr:1 row_mask:0xf bank_mask:0xf bound_ctrl:1
	v_fmac_f32_dpp v225, v43, v135 row_shr:1 row_mask:0xf bank_mask:0xf bound_ctrl:1
	v_fmac_f32_dpp v226, v44, v136 row_shr:1 row_mask:0xf bank_mask:0xf bound_ctrl:1
	v_fmac_f32_dpp v227, v45, v137 row_shr:1 row_mask:0xf bank_mask:0xf bound_ctrl:1
	v_fmac_f32_dpp v228, v14, v150 row_shr:1 row_mask:0xf bank_mask:0xf bound_ctrl:1
	v_fmac_f32_dpp v229, v15, v151 row_shr:1 row_mask:0xf bank_mask:0xf bound_ctrl:1
	v_fmac_f32_dpp v230, v16, v152 row_shr:1 row_mask:0xf bank_mask:0xf bound_ctrl:1
	v_fmac_f32_dpp v231, v17, v153 row_shr:1 row_mask:0xf bank_mask:0xf bound_ctrl:1
	v_fmac_f32_dpp v224, v42, v130 row_shr:2 row_mask:0xf bank_mask:0xf bound_ctrl:1
	v_fmac_f32_dpp v225, v43, v131 row_shr:2 row_mask:0xf bank_mask:0xf bound_ctrl:1
	v_fmac_f32_dpp v226, v44, v132 row_shr:2 row_mask:0xf bank_mask:0xf bound_ctrl:1
	v_fmac_f32_dpp v227, v45, v133 row_shr:2 row_mask:0xf bank_mask:0xf bound_ctrl:1
	v_fmac_f32_dpp v228, v14, v146 row_shr:2 row_mask:0xf bank_mask:0xf bound_ctrl:1
	v_fmac_f32_dpp v229, v15, v147 row_shr:2 row_mask:0xf bank_mask:0xf bound_ctrl:1
	v_fmac_f32_dpp v230, v16, v148 row_shr:2 row_mask:0xf bank_mask:0xf bound_ctrl:1
	v_fmac_f32_dpp v231, v17, v149 row_shr:2 row_mask:0xf bank_mask:0xf bound_ctrl:1
	v_fmac_f32_dpp v224, v54, v134 row_shl:15 row_mask:0xf bank_mask:0xf bound_ctrl:1
	v_fmac_f32_dpp v225, v55, v135 row_shl:15 row_mask:0xf bank_mask:0xf bound_ctrl:1
	v_fmac_f32_dpp v226, v56, v136 row_shl:15 row_mask:0xf bank_mask:0xf bound_ctrl:1
	v_fmac_f32_dpp v227, v57, v137 row_shl:15 row_mask:0xf bank_mask:0xf bound_ctrl:1
	v_fmac_f32_dpp v228, v30, v150 row_shl:15 row_mask:0xf bank_mask:0xf bound_ctrl:1
	v_fmac_f32_dpp v229, v31, v151 row_shl:15 row_mask:0xf bank_mask:0xf bound_ctrl:1
	v_fmac_f32_dpp v230, v32, v152 row_shl:15 row_mask:0xf bank_mask:0xf bound_ctrl:1
	v_fmac_f32_dpp v231, v33, v153 row_shl:15 row_mask:0xf bank_mask:0xf bound_ctrl:1
	v_fmac_f32_dpp v224, v54, v130 row_shl:14 row_mask:0xf bank_mask:0xf bound_ctrl:1
	v_fmac_f32_dpp v225, v55, v131 row_shl:14 row_mask:0xf bank_mask:0xf bound_ctrl:1
	v_fmac_f32_dpp v226, v56, v132 row_shl:14 row_mask:0xf bank_mask:0xf bound_ctrl:1
	v_fmac_f32_dpp v227, v57, v133 row_shl:14 row_mask:0xf bank_mask:0xf bound_ctrl:1
	v_fmac_f32_dpp v228, v30, v146 row_shl:14 row_mask:0xf bank_mask:0xf bound_ctrl:1
	v_fmac_f32_dpp v229, v31, v147 row_shl:14 row_mask:0xf bank_mask:0xf bound_ctrl:1
	v_fmac_f32_dpp v230, v32, v148 row_shl:14 row_mask:0xf bank_mask:0xf bound_ctrl:1
	v_fmac_f32_dpp v231, v33, v149 row_shl:14 row_mask:0xf bank_mask:0xf bound_ctrl:1
	v_pk_mul_f32 v[232:233], v[224:225], s[48:49] op_sel_hi:[1,0]
	v_pk_mul_f32 v[234:235], v[226:227], s[48:49] op_sel_hi:[1,0]
	v_exp_f32_e32 v232, v232
	v_exp_f32_e32 v233, v233
	v_exp_f32_e32 v234, v234
	v_exp_f32_e32 v235, v235
	s_nop 0
	v_pk_add_f32 v[232:233], v[232:233], 1.0 op_sel_hi:[1,0]
	v_pk_add_f32 v[234:235], v[234:235], 1.0 op_sel_hi:[1,0]
	v_rcp_f32_e32 v232, v232
	v_rcp_f32_e32 v233, v233
	v_rcp_f32_e32 v234, v234
	v_rcp_f32_e32 v235, v235
	v_lshl_add_u64 v[220:221], v[220:221], 0, s[96:97]
	v_pk_mul_f32 v[224:225], v[224:225], v[232:233]
	v_pk_mul_f32 v[226:227], v[226:227], v[234:235]
	v_pk_mul_f32 v[224:225], v[224:225], v[228:229]
	v_pk_mul_f32 v[226:227], v[226:227], v[230:231]
	s_nop 0
	v_cvt_pk_bf16_f32 v168, v224, v225
	v_cvt_pk_bf16_f32 v169, v226, v227
	global_store_dwordx2 v[220:221], v[168:169], off
	s_add_u32 s94, s26, s85
	s_addc_u32 s95, s27, 0
	v_lshl_add_u64 v[222:223], s[94:95], 0, v[216:217]
	v_lshl_add_u64 v[246:247], s[94:95], 0, v[218:219]
	s_and_saveexec_b64 s[46:47], s[6:7]
	global_store_dwordx4 v[222:223], v[26:29], off
	global_store_dwordx4 v[246:247], v[6:9], off
	s_or_b64 exec, exec, s[46:47]
	v_pk_fma_f32 v[224:225], v[26:27], v[138:139], v[142:143]
	v_pk_fma_f32 v[226:227], v[28:29], v[140:141], v[144:145]
	v_pk_fma_f32 v[228:229], v[6:7], v[154:155], v[158:159]
	v_pk_fma_f32 v[230:231], v[8:9], v[156:157], v[160:161]
	v_fmac_f32_dpp v224, v26, v134 row_shr:1 row_mask:0xf bank_mask:0xf bound_ctrl:1
	v_fmac_f32_dpp v225, v27, v135 row_shr:1 row_mask:0xf bank_mask:0xf bound_ctrl:1
	v_fmac_f32_dpp v226, v28, v136 row_shr:1 row_mask:0xf bank_mask:0xf bound_ctrl:1
	v_fmac_f32_dpp v227, v29, v137 row_shr:1 row_mask:0xf bank_mask:0xf bound_ctrl:1
	v_fmac_f32_dpp v228, v6, v150 row_shr:1 row_mask:0xf bank_mask:0xf bound_ctrl:1
	v_fmac_f32_dpp v229, v7, v151 row_shr:1 row_mask:0xf bank_mask:0xf bound_ctrl:1
	v_fmac_f32_dpp v230, v8, v152 row_shr:1 row_mask:0xf bank_mask:0xf bound_ctrl:1
	v_fmac_f32_dpp v231, v9, v153 row_shr:1 row_mask:0xf bank_mask:0xf bound_ctrl:1
	v_fmac_f32_dpp v224, v26, v130 row_shr:2 row_mask:0xf bank_mask:0xf bound_ctrl:1
	v_fmac_f32_dpp v225, v27, v131 row_shr:2 row_mask:0xf bank_mask:0xf bound_ctrl:1
	v_fmac_f32_dpp v226, v28, v132 row_shr:2 row_mask:0xf bank_mask:0xf bound_ctrl:1
	v_fmac_f32_dpp v227, v29, v133 row_shr:2 row_mask:0xf bank_mask:0xf bound_ctrl:1
	v_fmac_f32_dpp v228, v6, v146 row_shr:2 row_mask:0xf bank_mask:0xf bound_ctrl:1
	v_fmac_f32_dpp v229, v7, v147 row_shr:2 row_mask:0xf bank_mask:0xf bound_ctrl:1
	v_fmac_f32_dpp v230, v8, v148 row_shr:2 row_mask:0xf bank_mask:0xf bound_ctrl:1
	v_fmac_f32_dpp v231, v9, v149 row_shr:2 row_mask:0xf bank_mask:0xf bound_ctrl:1
	v_fmac_f32_dpp v224, v42, v134 row_shl:15 row_mask:0xf bank_mask:0xf bound_ctrl:1
	v_fmac_f32_dpp v225, v43, v135 row_shl:15 row_mask:0xf bank_mask:0xf bound_ctrl:1
	v_fmac_f32_dpp v226, v44, v136 row_shl:15 row_mask:0xf bank_mask:0xf bound_ctrl:1
	v_fmac_f32_dpp v227, v45, v137 row_shl:15 row_mask:0xf bank_mask:0xf bound_ctrl:1
	v_fmac_f32_dpp v228, v14, v150 row_shl:15 row_mask:0xf bank_mask:0xf bound_ctrl:1
	v_fmac_f32_dpp v229, v15, v151 row_shl:15 row_mask:0xf bank_mask:0xf bound_ctrl:1
	v_fmac_f32_dpp v230, v16, v152 row_shl:15 row_mask:0xf bank_mask:0xf bound_ctrl:1
	v_fmac_f32_dpp v231, v17, v153 row_shl:15 row_mask:0xf bank_mask:0xf bound_ctrl:1
	v_fmac_f32_dpp v224, v42, v130 row_shl:14 row_mask:0xf bank_mask:0xf bound_ctrl:1
	v_fmac_f32_dpp v225, v43, v131 row_shl:14 row_mask:0xf bank_mask:0xf bound_ctrl:1
	v_fmac_f32_dpp v226, v44, v132 row_shl:14 row_mask:0xf bank_mask:0xf bound_ctrl:1
	v_fmac_f32_dpp v227, v45, v133 row_shl:14 row_mask:0xf bank_mask:0xf bound_ctrl:1
	v_fmac_f32_dpp v228, v14, v146 row_shl:14 row_mask:0xf bank_mask:0xf bound_ctrl:1
	v_fmac_f32_dpp v229, v15, v147 row_shl:14 row_mask:0xf bank_mask:0xf bound_ctrl:1
	v_fmac_f32_dpp v230, v16, v148 row_shl:14 row_mask:0xf bank_mask:0xf bound_ctrl:1
	v_fmac_f32_dpp v231, v17, v149 row_shl:14 row_mask:0xf bank_mask:0xf bound_ctrl:1
	v_pk_mul_f32 v[232:233], v[224:225], s[48:49] op_sel_hi:[1,0]
	v_pk_mul_f32 v[234:235], v[226:227], s[48:49] op_sel_hi:[1,0]
	v_exp_f32_e32 v232, v232
	v_exp_f32_e32 v233, v233
	v_exp_f32_e32 v234, v234
	v_exp_f32_e32 v235, v235
	s_nop 0
	v_pk_add_f32 v[232:233], v[232:233], 1.0 op_sel_hi:[1,0]
	v_pk_add_f32 v[234:235], v[234:235], 1.0 op_sel_hi:[1,0]
	v_rcp_f32_e32 v232, v232
	v_rcp_f32_e32 v233, v233
	v_rcp_f32_e32 v234, v234
	v_rcp_f32_e32 v235, v235
	v_lshl_add_u64 v[220:221], v[220:221], 0, s[96:97]
	v_pk_mul_f32 v[224:225], v[224:225], v[232:233]
	v_pk_mul_f32 v[226:227], v[226:227], v[234:235]
	v_pk_mul_f32 v[224:225], v[224:225], v[228:229]
	v_pk_mul_f32 v[226:227], v[226:227], v[230:231]
	s_nop 0
	v_cvt_pk_bf16_f32 v168, v224, v225
	v_cvt_pk_bf16_f32 v169, v226, v227
	global_store_dwordx2 v[220:221], v[168:169], off
	s_add_i32 s84, s39, 0
	s_mul_i32 s85, s84, 0xb0000
	s_add_u32 s94, s22, s85
	s_addc_u32 s95, s23, 0
	v_lshl_add_u64 v[220:221], s[94:95], 0, v[210:211]
	s_mul_i32 s85, s84, 0x16000
	s_add_u32 s94, s24, s85
	s_addc_u32 s95, s25, 0
	v_lshl_add_u64 v[222:223], s[94:95], 0, v[212:213]
	v_lshl_add_u64 v[246:247], s[94:95], 0, v[214:215]
	s_and_saveexec_b64 s[46:47], s[4:5]
	global_store_dwordx4 v[222:223], v[122:125], off offset:64
	global_store_dwordx4 v[246:247], v[102:105], off offset:64
	s_or_b64 exec, exec, s[46:47]
	v_pk_fma_f32 v[224:225], v[122:123], v[186:187], v[190:191]
	v_pk_fma_f32 v[226:227], v[124:125], v[188:189], v[192:193]
	v_pk_fma_f32 v[228:229], v[102:103], v[202:203], v[206:207]
	v_pk_fma_f32 v[230:231], v[104:105], v[204:205], v[208:209]
	v_fmac_f32_dpp v224, v122, v182 row_shr:1 row_mask:0xf bank_mask:0xf bound_ctrl:1
	v_fmac_f32_dpp v225, v123, v183 row_shr:1 row_mask:0xf bank_mask:0xf bound_ctrl:1
	v_fmac_f32_dpp v226, v124, v184 row_shr:1 row_mask:0xf bank_mask:0xf bound_ctrl:1
	v_fmac_f32_dpp v227, v125, v185 row_shr:1 row_mask:0xf bank_mask:0xf bound_ctrl:1
	v_fmac_f32_dpp v228, v102, v198 row_shr:1 row_mask:0xf bank_mask:0xf bound_ctrl:1
	v_fmac_f32_dpp v229, v103, v199 row_shr:1 row_mask:0xf bank_mask:0xf bound_ctrl:1
	v_fmac_f32_dpp v230, v104, v200 row_shr:1 row_mask:0xf bank_mask:0xf bound_ctrl:1
	v_fmac_f32_dpp v231, v105, v201 row_shr:1 row_mask:0xf bank_mask:0xf bound_ctrl:1
	v_fmac_f32_dpp v224, v122, v178 row_shr:2 row_mask:0xf bank_mask:0xf bound_ctrl:1
	v_fmac_f32_dpp v225, v123, v179 row_shr:2 row_mask:0xf bank_mask:0xf bound_ctrl:1
	v_fmac_f32_dpp v226, v124, v180 row_shr:2 row_mask:0xf bank_mask:0xf bound_ctrl:1
	v_fmac_f32_dpp v227, v125, v181 row_shr:2 row_mask:0xf bank_mask:0xf bound_ctrl:1
	v_fmac_f32_dpp v228, v102, v194 row_shr:2 row_mask:0xf bank_mask:0xf bound_ctrl:1
	v_fmac_f32_dpp v229, v103, v195 row_shr:2 row_mask:0xf bank_mask:0xf bound_ctrl:1
	v_fmac_f32_dpp v230, v104, v196 row_shr:2 row_mask:0xf bank_mask:0xf bound_ctrl:1
	v_fmac_f32_dpp v231, v105, v197 row_shr:2 row_mask:0xf bank_mask:0xf bound_ctrl:1
	v_pk_mul_f32 v[232:233], v[224:225], s[48:49] op_sel_hi:[1,0]
	v_pk_mul_f32 v[234:235], v[226:227], s[48:49] op_sel_hi:[1,0]
	v_exp_f32_e32 v232, v232
	v_exp_f32_e32 v233, v233
	v_exp_f32_e32 v234, v234
	v_exp_f32_e32 v235, v235
	s_nop 0
	v_pk_add_f32 v[232:233], v[232:233], 1.0 op_sel_hi:[1,0]
	v_pk_add_f32 v[234:235], v[234:235], 1.0 op_sel_hi:[1,0]
	v_rcp_f32_e32 v232, v232
	v_rcp_f32_e32 v233, v233
	v_rcp_f32_e32 v234, v234
	v_rcp_f32_e32 v235, v235
	s_nop 0
	v_pk_mul_f32 v[224:225], v[224:225], v[232:233]
	v_pk_mul_f32 v[226:227], v[226:227], v[234:235]
	v_pk_mul_f32 v[224:225], v[224:225], v[228:229]
	v_pk_mul_f32 v[226:227], v[226:227], v[230:231]
	s_nop 0
	v_cvt_pk_bf16_f32 v168, v224, v225
	v_cvt_pk_bf16_f32 v169, v226, v227
	s_and_saveexec_b64 s[46:47], s[8:9]
	global_store_dwordx2 v[220:221], v[168:169], off offset:32
	s_or_b64 exec, exec, s[46:47]
	v_pk_fma_f32 v[224:225], v[114:115], v[186:187], v[190:191]
	v_pk_fma_f32 v[226:227], v[116:117], v[188:189], v[192:193]
	v_pk_fma_f32 v[228:229], v[86:87], v[202:203], v[206:207]
	v_pk_fma_f32 v[230:231], v[88:89], v[204:205], v[208:209]
	v_fmac_f32_dpp v224, v114, v182 row_shr:1 row_mask:0xf bank_mask:0xf bound_ctrl:1
	v_fmac_f32_dpp v225, v115, v183 row_shr:1 row_mask:0xf bank_mask:0xf bound_ctrl:1
	v_fmac_f32_dpp v226, v116, v184 row_shr:1 row_mask:0xf bank_mask:0xf bound_ctrl:1
	v_fmac_f32_dpp v227, v117, v185 row_shr:1 row_mask:0xf bank_mask:0xf bound_ctrl:1
	v_fmac_f32_dpp v228, v86, v198 row_shr:1 row_mask:0xf bank_mask:0xf bound_ctrl:1
	v_fmac_f32_dpp v229, v87, v199 row_shr:1 row_mask:0xf bank_mask:0xf bound_ctrl:1
	v_fmac_f32_dpp v230, v88, v200 row_shr:1 row_mask:0xf bank_mask:0xf bound_ctrl:1
	v_fmac_f32_dpp v231, v89, v201 row_shr:1 row_mask:0xf bank_mask:0xf bound_ctrl:1
	v_fmac_f32_dpp v224, v114, v178 row_shr:2 row_mask:0xf bank_mask:0xf bound_ctrl:1
	v_fmac_f32_dpp v225, v115, v179 row_shr:2 row_mask:0xf bank_mask:0xf bound_ctrl:1
	v_fmac_f32_dpp v226, v116, v180 row_shr:2 row_mask:0xf bank_mask:0xf bound_ctrl:1
	v_fmac_f32_dpp v227, v117, v181 row_shr:2 row_mask:0xf bank_mask:0xf bound_ctrl:1
	v_fmac_f32_dpp v228, v86, v194 row_shr:2 row_mask:0xf bank_mask:0xf bound_ctrl:1
	v_fmac_f32_dpp v229, v87, v195 row_shr:2 row_mask:0xf bank_mask:0xf bound_ctrl:1
	v_fmac_f32_dpp v230, v88, v196 row_shr:2 row_mask:0xf bank_mask:0xf bound_ctrl:1
	v_fmac_f32_dpp v231, v89, v197 row_shr:2 row_mask:0xf bank_mask:0xf bound_ctrl:1
	v_fmac_f32_dpp v224, v122, v182 row_shl:15 row_mask:0xf bank_mask:0xf bound_ctrl:1
	v_fmac_f32_dpp v225, v123, v183 row_shl:15 row_mask:0xf bank_mask:0xf bound_ctrl:1
	v_fmac_f32_dpp v226, v124, v184 row_shl:15 row_mask:0xf bank_mask:0xf bound_ctrl:1
	v_fmac_f32_dpp v227, v125, v185 row_shl:15 row_mask:0xf bank_mask:0xf bound_ctrl:1
	v_fmac_f32_dpp v228, v102, v198 row_shl:15 row_mask:0xf bank_mask:0xf bound_ctrl:1
	v_fmac_f32_dpp v229, v103, v199 row_shl:15 row_mask:0xf bank_mask:0xf bound_ctrl:1
	v_fmac_f32_dpp v230, v104, v200 row_shl:15 row_mask:0xf bank_mask:0xf bound_ctrl:1
	v_fmac_f32_dpp v231, v105, v201 row_shl:15 row_mask:0xf bank_mask:0xf bound_ctrl:1
	v_fmac_f32_dpp v224, v122, v178 row_shl:14 row_mask:0xf bank_mask:0xf bound_ctrl:1
	v_fmac_f32_dpp v225, v123, v179 row_shl:14 row_mask:0xf bank_mask:0xf bound_ctrl:1
	v_fmac_f32_dpp v226, v124, v180 row_shl:14 row_mask:0xf bank_mask:0xf bound_ctrl:1
	v_fmac_f32_dpp v227, v125, v181 row_shl:14 row_mask:0xf bank_mask:0xf bound_ctrl:1
	v_fmac_f32_dpp v228, v102, v194 row_shl:14 row_mask:0xf bank_mask:0xf bound_ctrl:1
	v_fmac_f32_dpp v229, v103, v195 row_shl:14 row_mask:0xf bank_mask:0xf bound_ctrl:1
	v_fmac_f32_dpp v230, v104, v196 row_shl:14 row_mask:0xf bank_mask:0xf bound_ctrl:1
	v_fmac_f32_dpp v231, v105, v197 row_shl:14 row_mask:0xf bank_mask:0xf bound_ctrl:1
	v_pk_mul_f32 v[232:233], v[224:225], s[48:49] op_sel_hi:[1,0]
	v_pk_mul_f32 v[234:235], v[226:227], s[48:49] op_sel_hi:[1,0]
	v_exp_f32_e32 v232, v232
	v_exp_f32_e32 v233, v233
	v_exp_f32_e32 v234, v234
	v_exp_f32_e32 v235, v235
	s_nop 0
	v_pk_add_f32 v[232:233], v[232:233], 1.0 op_sel_hi:[1,0]
	v_pk_add_f32 v[234:235], v[234:235], 1.0 op_sel_hi:[1,0]
	v_rcp_f32_e32 v232, v232
	v_rcp_f32_e32 v233, v233
	v_rcp_f32_e32 v234, v234
	v_rcp_f32_e32 v235, v235
	v_lshl_add_u64 v[220:221], v[220:221], 0, s[96:97]
	v_pk_mul_f32 v[224:225], v[224:225], v[232:233]
	v_pk_mul_f32 v[226:227], v[226:227], v[234:235]
	v_pk_mul_f32 v[224:225], v[224:225], v[228:229]
	v_pk_mul_f32 v[226:227], v[226:227], v[230:231]
	s_nop 0
	v_cvt_pk_bf16_f32 v168, v224, v225
	v_cvt_pk_bf16_f32 v169, v226, v227
	global_store_dwordx2 v[220:221], v[168:169], off offset:32
	v_pk_fma_f32 v[224:225], v[98:99], v[186:187], v[190:191]
	v_pk_fma_f32 v[226:227], v[100:101], v[188:189], v[192:193]
	v_pk_fma_f32 v[228:229], v[74:75], v[202:203], v[206:207]
	v_pk_fma_f32 v[230:231], v[76:77], v[204:205], v[208:209]
	v_fmac_f32_dpp v224, v98, v182 row_shr:1 row_mask:0xf bank_mask:0xf bound_ctrl:1
	v_fmac_f32_dpp v225, v99, v183 row_shr:1 row_mask:0xf bank_mask:0xf bound_ctrl:1
	v_fmac_f32_dpp v226, v100, v184 row_shr:1 row_mask:0xf bank_mask:0xf bound_ctrl:1
	v_fmac_f32_dpp v227, v101, v185 row_shr:1 row_mask:0xf bank_mask:0xf bound_ctrl:1
	v_fmac_f32_dpp v228, v74, v198 row_shr:1 row_mask:0xf bank_mask:0xf bound_ctrl:1
	v_fmac_f32_dpp v229, v75, v199 row_shr:1 row_mask:0xf bank_mask:0xf bound_ctrl:1
	v_fmac_f32_dpp v230, v76, v200 row_shr:1 row_mask:0xf bank_mask:0xf bound_ctrl:1
	v_fmac_f32_dpp v231, v77, v201 row_shr:1 row_mask:0xf bank_mask:0xf bound_ctrl:1
	v_fmac_f32_dpp v224, v98, v178 row_shr:2 row_mask:0xf bank_mask:0xf bound_ctrl:1
	v_fmac_f32_dpp v225, v99, v179 row_shr:2 row_mask:0xf bank_mask:0xf bound_ctrl:1
	v_fmac_f32_dpp v226, v100, v180 row_shr:2 row_mask:0xf bank_mask:0xf bound_ctrl:1
	v_fmac_f32_dpp v227, v101, v181 row_shr:2 row_mask:0xf bank_mask:0xf bound_ctrl:1
	v_fmac_f32_dpp v228, v74, v194 row_shr:2 row_mask:0xf bank_mask:0xf bound_ctrl:1
	v_fmac_f32_dpp v229, v75, v195 row_shr:2 row_mask:0xf bank_mask:0xf bound_ctrl:1
	v_fmac_f32_dpp v230, v76, v196 row_shr:2 row_mask:0xf bank_mask:0xf bound_ctrl:1
	v_fmac_f32_dpp v231, v77, v197 row_shr:2 row_mask:0xf bank_mask:0xf bound_ctrl:1
	v_fmac_f32_dpp v224, v114, v182 row_shl:15 row_mask:0xf bank_mask:0xf bound_ctrl:1
	v_fmac_f32_dpp v225, v115, v183 row_shl:15 row_mask:0xf bank_mask:0xf bound_ctrl:1
	v_fmac_f32_dpp v226, v116, v184 row_shl:15 row_mask:0xf bank_mask:0xf bound_ctrl:1
	v_fmac_f32_dpp v227, v117, v185 row_shl:15 row_mask:0xf bank_mask:0xf bound_ctrl:1
	v_fmac_f32_dpp v228, v86, v198 row_shl:15 row_mask:0xf bank_mask:0xf bound_ctrl:1
	v_fmac_f32_dpp v229, v87, v199 row_shl:15 row_mask:0xf bank_mask:0xf bound_ctrl:1
	v_fmac_f32_dpp v230, v88, v200 row_shl:15 row_mask:0xf bank_mask:0xf bound_ctrl:1
	v_fmac_f32_dpp v231, v89, v201 row_shl:15 row_mask:0xf bank_mask:0xf bound_ctrl:1
	v_fmac_f32_dpp v224, v114, v178 row_shl:14 row_mask:0xf bank_mask:0xf bound_ctrl:1
	v_fmac_f32_dpp v225, v115, v179 row_shl:14 row_mask:0xf bank_mask:0xf bound_ctrl:1
	v_fmac_f32_dpp v226, v116, v180 row_shl:14 row_mask:0xf bank_mask:0xf bound_ctrl:1
	v_fmac_f32_dpp v227, v117, v181 row_shl:14 row_mask:0xf bank_mask:0xf bound_ctrl:1
	v_fmac_f32_dpp v228, v86, v194 row_shl:14 row_mask:0xf bank_mask:0xf bound_ctrl:1
	v_fmac_f32_dpp v229, v87, v195 row_shl:14 row_mask:0xf bank_mask:0xf bound_ctrl:1
	v_fmac_f32_dpp v230, v88, v196 row_shl:14 row_mask:0xf bank_mask:0xf bound_ctrl:1
	v_fmac_f32_dpp v231, v89, v197 row_shl:14 row_mask:0xf bank_mask:0xf bound_ctrl:1
	v_pk_mul_f32 v[232:233], v[224:225], s[48:49] op_sel_hi:[1,0]
	v_pk_mul_f32 v[234:235], v[226:227], s[48:49] op_sel_hi:[1,0]
	v_exp_f32_e32 v232, v232
	v_exp_f32_e32 v233, v233
	v_exp_f32_e32 v234, v234
	v_exp_f32_e32 v235, v235
	s_nop 0
	v_pk_add_f32 v[232:233], v[232:233], 1.0 op_sel_hi:[1,0]
	v_pk_add_f32 v[234:235], v[234:235], 1.0 op_sel_hi:[1,0]
	v_rcp_f32_e32 v232, v232
	v_rcp_f32_e32 v233, v233
	v_rcp_f32_e32 v234, v234
	v_rcp_f32_e32 v235, v235
	v_lshl_add_u64 v[220:221], v[220:221], 0, s[96:97]
	v_pk_mul_f32 v[224:225], v[224:225], v[232:233]
	v_pk_mul_f32 v[226:227], v[226:227], v[234:235]
	v_pk_mul_f32 v[224:225], v[224:225], v[228:229]
	v_pk_mul_f32 v[226:227], v[226:227], v[230:231]
	s_nop 0
	v_cvt_pk_bf16_f32 v168, v224, v225
	v_cvt_pk_bf16_f32 v169, v226, v227
	global_store_dwordx2 v[220:221], v[168:169], off offset:32
	s_add_u32 s94, s26, s85
	s_addc_u32 s95, s27, 0
	v_lshl_add_u64 v[222:223], s[94:95], 0, v[216:217]
	v_lshl_add_u64 v[246:247], s[94:95], 0, v[218:219]
	s_and_saveexec_b64 s[46:47], s[6:7]
	global_store_dwordx4 v[222:223], v[82:85], off offset:64
	global_store_dwordx4 v[246:247], v[66:69], off offset:64
	s_or_b64 exec, exec, s[46:47]
	v_pk_fma_f32 v[224:225], v[82:83], v[186:187], v[190:191]
	v_pk_fma_f32 v[226:227], v[84:85], v[188:189], v[192:193]
	v_pk_fma_f32 v[228:229], v[66:67], v[202:203], v[206:207]
	v_pk_fma_f32 v[230:231], v[68:69], v[204:205], v[208:209]
	v_fmac_f32_dpp v224, v82, v182 row_shr:1 row_mask:0xf bank_mask:0xf bound_ctrl:1
	v_fmac_f32_dpp v225, v83, v183 row_shr:1 row_mask:0xf bank_mask:0xf bound_ctrl:1
	v_fmac_f32_dpp v226, v84, v184 row_shr:1 row_mask:0xf bank_mask:0xf bound_ctrl:1
	v_fmac_f32_dpp v227, v85, v185 row_shr:1 row_mask:0xf bank_mask:0xf bound_ctrl:1
	v_fmac_f32_dpp v228, v66, v198 row_shr:1 row_mask:0xf bank_mask:0xf bound_ctrl:1
	v_fmac_f32_dpp v229, v67, v199 row_shr:1 row_mask:0xf bank_mask:0xf bound_ctrl:1
	v_fmac_f32_dpp v230, v68, v200 row_shr:1 row_mask:0xf bank_mask:0xf bound_ctrl:1
	v_fmac_f32_dpp v231, v69, v201 row_shr:1 row_mask:0xf bank_mask:0xf bound_ctrl:1
	v_fmac_f32_dpp v224, v82, v178 row_shr:2 row_mask:0xf bank_mask:0xf bound_ctrl:1
	v_fmac_f32_dpp v225, v83, v179 row_shr:2 row_mask:0xf bank_mask:0xf bound_ctrl:1
	v_fmac_f32_dpp v226, v84, v180 row_shr:2 row_mask:0xf bank_mask:0xf bound_ctrl:1
	v_fmac_f32_dpp v227, v85, v181 row_shr:2 row_mask:0xf bank_mask:0xf bound_ctrl:1
	v_fmac_f32_dpp v228, v66, v194 row_shr:2 row_mask:0xf bank_mask:0xf bound_ctrl:1
	v_fmac_f32_dpp v229, v67, v195 row_shr:2 row_mask:0xf bank_mask:0xf bound_ctrl:1
	v_fmac_f32_dpp v230, v68, v196 row_shr:2 row_mask:0xf bank_mask:0xf bound_ctrl:1
	v_fmac_f32_dpp v231, v69, v197 row_shr:2 row_mask:0xf bank_mask:0xf bound_ctrl:1
	v_fmac_f32_dpp v224, v98, v182 row_shl:15 row_mask:0xf bank_mask:0xf bound_ctrl:1
	v_fmac_f32_dpp v225, v99, v183 row_shl:15 row_mask:0xf bank_mask:0xf bound_ctrl:1
	v_fmac_f32_dpp v226, v100, v184 row_shl:15 row_mask:0xf bank_mask:0xf bound_ctrl:1
	v_fmac_f32_dpp v227, v101, v185 row_shl:15 row_mask:0xf bank_mask:0xf bound_ctrl:1
	v_fmac_f32_dpp v228, v74, v198 row_shl:15 row_mask:0xf bank_mask:0xf bound_ctrl:1
	v_fmac_f32_dpp v229, v75, v199 row_shl:15 row_mask:0xf bank_mask:0xf bound_ctrl:1
	v_fmac_f32_dpp v230, v76, v200 row_shl:15 row_mask:0xf bank_mask:0xf bound_ctrl:1
	v_fmac_f32_dpp v231, v77, v201 row_shl:15 row_mask:0xf bank_mask:0xf bound_ctrl:1
	v_fmac_f32_dpp v224, v98, v178 row_shl:14 row_mask:0xf bank_mask:0xf bound_ctrl:1
	v_fmac_f32_dpp v225, v99, v179 row_shl:14 row_mask:0xf bank_mask:0xf bound_ctrl:1
	v_fmac_f32_dpp v226, v100, v180 row_shl:14 row_mask:0xf bank_mask:0xf bound_ctrl:1
	v_fmac_f32_dpp v227, v101, v181 row_shl:14 row_mask:0xf bank_mask:0xf bound_ctrl:1
	v_fmac_f32_dpp v228, v74, v194 row_shl:14 row_mask:0xf bank_mask:0xf bound_ctrl:1
	v_fmac_f32_dpp v229, v75, v195 row_shl:14 row_mask:0xf bank_mask:0xf bound_ctrl:1
	v_fmac_f32_dpp v230, v76, v196 row_shl:14 row_mask:0xf bank_mask:0xf bound_ctrl:1
	v_fmac_f32_dpp v231, v77, v197 row_shl:14 row_mask:0xf bank_mask:0xf bound_ctrl:1
	v_pk_mul_f32 v[232:233], v[224:225], s[48:49] op_sel_hi:[1,0]
	v_pk_mul_f32 v[234:235], v[226:227], s[48:49] op_sel_hi:[1,0]
	v_exp_f32_e32 v232, v232
	v_exp_f32_e32 v233, v233
	v_exp_f32_e32 v234, v234
	v_exp_f32_e32 v235, v235
	s_nop 0
	v_pk_add_f32 v[232:233], v[232:233], 1.0 op_sel_hi:[1,0]
	v_pk_add_f32 v[234:235], v[234:235], 1.0 op_sel_hi:[1,0]
	v_rcp_f32_e32 v232, v232
	v_rcp_f32_e32 v233, v233
	v_rcp_f32_e32 v234, v234
	v_rcp_f32_e32 v235, v235
	v_lshl_add_u64 v[220:221], v[220:221], 0, s[96:97]
	v_pk_mul_f32 v[224:225], v[224:225], v[232:233]
	v_pk_mul_f32 v[226:227], v[226:227], v[234:235]
	v_pk_mul_f32 v[224:225], v[224:225], v[228:229]
	v_pk_mul_f32 v[226:227], v[226:227], v[230:231]
	s_nop 0
	v_cvt_pk_bf16_f32 v168, v224, v225
	v_cvt_pk_bf16_f32 v169, v226, v227
	global_store_dwordx2 v[220:221], v[168:169], off offset:32
	s_add_i32 s84, s39, 2
	s_mul_i32 s85, s84, 0xb0000
	s_add_u32 s94, s22, s85
	s_addc_u32 s95, s23, 0
	v_lshl_add_u64 v[220:221], s[94:95], 0, v[210:211]
	s_mul_i32 s85, s84, 0x16000
	s_add_u32 s94, s24, s85
	s_addc_u32 s95, s25, 0
	v_lshl_add_u64 v[222:223], s[94:95], 0, v[212:213]
	v_lshl_add_u64 v[246:247], s[94:95], 0, v[214:215]
	s_and_saveexec_b64 s[46:47], s[4:5]
	global_store_dwordx4 v[222:223], v[58:61], off offset:64
	global_store_dwordx4 v[246:247], v[38:41], off offset:64
	s_or_b64 exec, exec, s[46:47]
	v_pk_fma_f32 v[224:225], v[58:59], v[186:187], v[190:191]
	v_pk_fma_f32 v[226:227], v[60:61], v[188:189], v[192:193]
	v_pk_fma_f32 v[228:229], v[38:39], v[202:203], v[206:207]
	v_pk_fma_f32 v[230:231], v[40:41], v[204:205], v[208:209]
	v_fmac_f32_dpp v224, v58, v182 row_shr:1 row_mask:0xf bank_mask:0xf bound_ctrl:1
	v_fmac_f32_dpp v225, v59, v183 row_shr:1 row_mask:0xf bank_mask:0xf bound_ctrl:1
	v_fmac_f32_dpp v226, v60, v184 row_shr:1 row_mask:0xf bank_mask:0xf bound_ctrl:1
	v_fmac_f32_dpp v227, v61, v185 row_shr:1 row_mask:0xf bank_mask:0xf bound_ctrl:1
	v_fmac_f32_dpp v228, v38, v198 row_shr:1 row_mask:0xf bank_mask:0xf bound_ctrl:1
	v_fmac_f32_dpp v229, v39, v199 row_shr:1 row_mask:0xf bank_mask:0xf bound_ctrl:1
	v_fmac_f32_dpp v230, v40, v200 row_shr:1 row_mask:0xf bank_mask:0xf bound_ctrl:1
	v_fmac_f32_dpp v231, v41, v201 row_shr:1 row_mask:0xf bank_mask:0xf bound_ctrl:1
	v_fmac_f32_dpp v224, v58, v178 row_shr:2 row_mask:0xf bank_mask:0xf bound_ctrl:1
	v_fmac_f32_dpp v225, v59, v179 row_shr:2 row_mask:0xf bank_mask:0xf bound_ctrl:1
	v_fmac_f32_dpp v226, v60, v180 row_shr:2 row_mask:0xf bank_mask:0xf bound_ctrl:1
	v_fmac_f32_dpp v227, v61, v181 row_shr:2 row_mask:0xf bank_mask:0xf bound_ctrl:1
	v_fmac_f32_dpp v228, v38, v194 row_shr:2 row_mask:0xf bank_mask:0xf bound_ctrl:1
	v_fmac_f32_dpp v229, v39, v195 row_shr:2 row_mask:0xf bank_mask:0xf bound_ctrl:1
	v_fmac_f32_dpp v230, v40, v196 row_shr:2 row_mask:0xf bank_mask:0xf bound_ctrl:1
	v_fmac_f32_dpp v231, v41, v197 row_shr:2 row_mask:0xf bank_mask:0xf bound_ctrl:1
	v_pk_mul_f32 v[232:233], v[224:225], s[48:49] op_sel_hi:[1,0]
	v_pk_mul_f32 v[234:235], v[226:227], s[48:49] op_sel_hi:[1,0]
	v_exp_f32_e32 v232, v232
	v_exp_f32_e32 v233, v233
	v_exp_f32_e32 v234, v234
	v_exp_f32_e32 v235, v235
	s_nop 0
	v_pk_add_f32 v[232:233], v[232:233], 1.0 op_sel_hi:[1,0]
	v_pk_add_f32 v[234:235], v[234:235], 1.0 op_sel_hi:[1,0]
	v_rcp_f32_e32 v232, v232
	v_rcp_f32_e32 v233, v233
	v_rcp_f32_e32 v234, v234
	v_rcp_f32_e32 v235, v235
	s_nop 0
	v_pk_mul_f32 v[224:225], v[224:225], v[232:233]
	v_pk_mul_f32 v[226:227], v[226:227], v[234:235]
	v_pk_mul_f32 v[224:225], v[224:225], v[228:229]
	v_pk_mul_f32 v[226:227], v[226:227], v[230:231]
	s_nop 0
	v_cvt_pk_bf16_f32 v168, v224, v225
	v_cvt_pk_bf16_f32 v169, v226, v227
	s_and_saveexec_b64 s[46:47], s[8:9]
	global_store_dwordx2 v[220:221], v[168:169], off offset:32
	s_or_b64 exec, exec, s[46:47]
	v_pk_fma_f32 v[224:225], v[50:51], v[186:187], v[190:191]
	v_pk_fma_f32 v[226:227], v[52:53], v[188:189], v[192:193]
	v_pk_fma_f32 v[228:229], v[22:23], v[202:203], v[206:207]
	v_pk_fma_f32 v[230:231], v[24:25], v[204:205], v[208:209]
	v_fmac_f32_dpp v224, v50, v182 row_shr:1 row_mask:0xf bank_mask:0xf bound_ctrl:1
	v_fmac_f32_dpp v225, v51, v183 row_shr:1 row_mask:0xf bank_mask:0xf bound_ctrl:1
	v_fmac_f32_dpp v226, v52, v184 row_shr:1 row_mask:0xf bank_mask:0xf bound_ctrl:1
	v_fmac_f32_dpp v227, v53, v185 row_shr:1 row_mask:0xf bank_mask:0xf bound_ctrl:1
	v_fmac_f32_dpp v228, v22, v198 row_shr:1 row_mask:0xf bank_mask:0xf bound_ctrl:1
	v_fmac_f32_dpp v229, v23, v199 row_shr:1 row_mask:0xf bank_mask:0xf bound_ctrl:1
	v_fmac_f32_dpp v230, v24, v200 row_shr:1 row_mask:0xf bank_mask:0xf bound_ctrl:1
	v_fmac_f32_dpp v231, v25, v201 row_shr:1 row_mask:0xf bank_mask:0xf bound_ctrl:1
	v_fmac_f32_dpp v224, v50, v178 row_shr:2 row_mask:0xf bank_mask:0xf bound_ctrl:1
	v_fmac_f32_dpp v225, v51, v179 row_shr:2 row_mask:0xf bank_mask:0xf bound_ctrl:1
	v_fmac_f32_dpp v226, v52, v180 row_shr:2 row_mask:0xf bank_mask:0xf bound_ctrl:1
	v_fmac_f32_dpp v227, v53, v181 row_shr:2 row_mask:0xf bank_mask:0xf bound_ctrl:1
	v_fmac_f32_dpp v228, v22, v194 row_shr:2 row_mask:0xf bank_mask:0xf bound_ctrl:1
	v_fmac_f32_dpp v229, v23, v195 row_shr:2 row_mask:0xf bank_mask:0xf bound_ctrl:1
	v_fmac_f32_dpp v230, v24, v196 row_shr:2 row_mask:0xf bank_mask:0xf bound_ctrl:1
	v_fmac_f32_dpp v231, v25, v197 row_shr:2 row_mask:0xf bank_mask:0xf bound_ctrl:1
	v_fmac_f32_dpp v224, v58, v182 row_shl:15 row_mask:0xf bank_mask:0xf bound_ctrl:1
	v_fmac_f32_dpp v225, v59, v183 row_shl:15 row_mask:0xf bank_mask:0xf bound_ctrl:1
	v_fmac_f32_dpp v226, v60, v184 row_shl:15 row_mask:0xf bank_mask:0xf bound_ctrl:1
	v_fmac_f32_dpp v227, v61, v185 row_shl:15 row_mask:0xf bank_mask:0xf bound_ctrl:1
	v_fmac_f32_dpp v228, v38, v198 row_shl:15 row_mask:0xf bank_mask:0xf bound_ctrl:1
	v_fmac_f32_dpp v229, v39, v199 row_shl:15 row_mask:0xf bank_mask:0xf bound_ctrl:1
	v_fmac_f32_dpp v230, v40, v200 row_shl:15 row_mask:0xf bank_mask:0xf bound_ctrl:1
	v_fmac_f32_dpp v231, v41, v201 row_shl:15 row_mask:0xf bank_mask:0xf bound_ctrl:1
	v_fmac_f32_dpp v224, v58, v178 row_shl:14 row_mask:0xf bank_mask:0xf bound_ctrl:1
	v_fmac_f32_dpp v225, v59, v179 row_shl:14 row_mask:0xf bank_mask:0xf bound_ctrl:1
	v_fmac_f32_dpp v226, v60, v180 row_shl:14 row_mask:0xf bank_mask:0xf bound_ctrl:1
	v_fmac_f32_dpp v227, v61, v181 row_shl:14 row_mask:0xf bank_mask:0xf bound_ctrl:1
	v_fmac_f32_dpp v228, v38, v194 row_shl:14 row_mask:0xf bank_mask:0xf bound_ctrl:1
	v_fmac_f32_dpp v229, v39, v195 row_shl:14 row_mask:0xf bank_mask:0xf bound_ctrl:1
	v_fmac_f32_dpp v230, v40, v196 row_shl:14 row_mask:0xf bank_mask:0xf bound_ctrl:1
	v_fmac_f32_dpp v231, v41, v197 row_shl:14 row_mask:0xf bank_mask:0xf bound_ctrl:1
	v_pk_mul_f32 v[232:233], v[224:225], s[48:49] op_sel_hi:[1,0]
	v_pk_mul_f32 v[234:235], v[226:227], s[48:49] op_sel_hi:[1,0]
	v_exp_f32_e32 v232, v232
	v_exp_f32_e32 v233, v233
	v_exp_f32_e32 v234, v234
	v_exp_f32_e32 v235, v235
	s_nop 0
	v_pk_add_f32 v[232:233], v[232:233], 1.0 op_sel_hi:[1,0]
	v_pk_add_f32 v[234:235], v[234:235], 1.0 op_sel_hi:[1,0]
	v_rcp_f32_e32 v232, v232
	v_rcp_f32_e32 v233, v233
	v_rcp_f32_e32 v234, v234
	v_rcp_f32_e32 v235, v235
	v_lshl_add_u64 v[220:221], v[220:221], 0, s[96:97]
	v_pk_mul_f32 v[224:225], v[224:225], v[232:233]
	v_pk_mul_f32 v[226:227], v[226:227], v[234:235]
	v_pk_mul_f32 v[224:225], v[224:225], v[228:229]
	v_pk_mul_f32 v[226:227], v[226:227], v[230:231]
	s_nop 0
	v_cvt_pk_bf16_f32 v168, v224, v225
	v_cvt_pk_bf16_f32 v169, v226, v227
	global_store_dwordx2 v[220:221], v[168:169], off offset:32
	v_pk_fma_f32 v[224:225], v[34:35], v[186:187], v[190:191]
	v_pk_fma_f32 v[226:227], v[36:37], v[188:189], v[192:193]
	v_pk_fma_f32 v[228:229], v[10:11], v[202:203], v[206:207]
	v_pk_fma_f32 v[230:231], v[12:13], v[204:205], v[208:209]
	v_fmac_f32_dpp v224, v34, v182 row_shr:1 row_mask:0xf bank_mask:0xf bound_ctrl:1
	v_fmac_f32_dpp v225, v35, v183 row_shr:1 row_mask:0xf bank_mask:0xf bound_ctrl:1
	v_fmac_f32_dpp v226, v36, v184 row_shr:1 row_mask:0xf bank_mask:0xf bound_ctrl:1
	v_fmac_f32_dpp v227, v37, v185 row_shr:1 row_mask:0xf bank_mask:0xf bound_ctrl:1
	v_fmac_f32_dpp v228, v10, v198 row_shr:1 row_mask:0xf bank_mask:0xf bound_ctrl:1
	v_fmac_f32_dpp v229, v11, v199 row_shr:1 row_mask:0xf bank_mask:0xf bound_ctrl:1
	v_fmac_f32_dpp v230, v12, v200 row_shr:1 row_mask:0xf bank_mask:0xf bound_ctrl:1
	v_fmac_f32_dpp v231, v13, v201 row_shr:1 row_mask:0xf bank_mask:0xf bound_ctrl:1
	v_fmac_f32_dpp v224, v34, v178 row_shr:2 row_mask:0xf bank_mask:0xf bound_ctrl:1
	v_fmac_f32_dpp v225, v35, v179 row_shr:2 row_mask:0xf bank_mask:0xf bound_ctrl:1
	v_fmac_f32_dpp v226, v36, v180 row_shr:2 row_mask:0xf bank_mask:0xf bound_ctrl:1
	v_fmac_f32_dpp v227, v37, v181 row_shr:2 row_mask:0xf bank_mask:0xf bound_ctrl:1
	v_fmac_f32_dpp v228, v10, v194 row_shr:2 row_mask:0xf bank_mask:0xf bound_ctrl:1
	v_fmac_f32_dpp v229, v11, v195 row_shr:2 row_mask:0xf bank_mask:0xf bound_ctrl:1
	v_fmac_f32_dpp v230, v12, v196 row_shr:2 row_mask:0xf bank_mask:0xf bound_ctrl:1
	v_fmac_f32_dpp v231, v13, v197 row_shr:2 row_mask:0xf bank_mask:0xf bound_ctrl:1
	v_fmac_f32_dpp v224, v50, v182 row_shl:15 row_mask:0xf bank_mask:0xf bound_ctrl:1
	v_fmac_f32_dpp v225, v51, v183 row_shl:15 row_mask:0xf bank_mask:0xf bound_ctrl:1
	v_fmac_f32_dpp v226, v52, v184 row_shl:15 row_mask:0xf bank_mask:0xf bound_ctrl:1
	v_fmac_f32_dpp v227, v53, v185 row_shl:15 row_mask:0xf bank_mask:0xf bound_ctrl:1
	v_fmac_f32_dpp v228, v22, v198 row_shl:15 row_mask:0xf bank_mask:0xf bound_ctrl:1
	v_fmac_f32_dpp v229, v23, v199 row_shl:15 row_mask:0xf bank_mask:0xf bound_ctrl:1
	v_fmac_f32_dpp v230, v24, v200 row_shl:15 row_mask:0xf bank_mask:0xf bound_ctrl:1
	v_fmac_f32_dpp v231, v25, v201 row_shl:15 row_mask:0xf bank_mask:0xf bound_ctrl:1
	v_fmac_f32_dpp v224, v50, v178 row_shl:14 row_mask:0xf bank_mask:0xf bound_ctrl:1
	v_fmac_f32_dpp v225, v51, v179 row_shl:14 row_mask:0xf bank_mask:0xf bound_ctrl:1
	v_fmac_f32_dpp v226, v52, v180 row_shl:14 row_mask:0xf bank_mask:0xf bound_ctrl:1
	v_fmac_f32_dpp v227, v53, v181 row_shl:14 row_mask:0xf bank_mask:0xf bound_ctrl:1
	v_fmac_f32_dpp v228, v22, v194 row_shl:14 row_mask:0xf bank_mask:0xf bound_ctrl:1
	v_fmac_f32_dpp v229, v23, v195 row_shl:14 row_mask:0xf bank_mask:0xf bound_ctrl:1
	v_fmac_f32_dpp v230, v24, v196 row_shl:14 row_mask:0xf bank_mask:0xf bound_ctrl:1
	v_fmac_f32_dpp v231, v25, v197 row_shl:14 row_mask:0xf bank_mask:0xf bound_ctrl:1
	v_pk_mul_f32 v[232:233], v[224:225], s[48:49] op_sel_hi:[1,0]
	v_pk_mul_f32 v[234:235], v[226:227], s[48:49] op_sel_hi:[1,0]
	v_exp_f32_e32 v232, v232
	v_exp_f32_e32 v233, v233
	v_exp_f32_e32 v234, v234
	v_exp_f32_e32 v235, v235
	s_nop 0
	v_pk_add_f32 v[232:233], v[232:233], 1.0 op_sel_hi:[1,0]
	v_pk_add_f32 v[234:235], v[234:235], 1.0 op_sel_hi:[1,0]
	v_rcp_f32_e32 v232, v232
	v_rcp_f32_e32 v233, v233
	v_rcp_f32_e32 v234, v234
	v_rcp_f32_e32 v235, v235
	v_lshl_add_u64 v[220:221], v[220:221], 0, s[96:97]
	v_pk_mul_f32 v[224:225], v[224:225], v[232:233]
	v_pk_mul_f32 v[226:227], v[226:227], v[234:235]
	v_pk_mul_f32 v[224:225], v[224:225], v[228:229]
	v_pk_mul_f32 v[226:227], v[226:227], v[230:231]
	s_nop 0
	v_cvt_pk_bf16_f32 v168, v224, v225
	v_cvt_pk_bf16_f32 v169, v226, v227
	global_store_dwordx2 v[220:221], v[168:169], off offset:32
	s_add_u32 s94, s26, s85
	s_addc_u32 s95, s27, 0
	v_lshl_add_u64 v[222:223], s[94:95], 0, v[216:217]
	v_lshl_add_u64 v[246:247], s[94:95], 0, v[218:219]
	s_and_saveexec_b64 s[46:47], s[6:7]
	global_store_dwordx4 v[222:223], v[18:21], off offset:64
	global_store_dwordx4 v[246:247], v[2:5], off offset:64
	s_or_b64 exec, exec, s[46:47]
	v_pk_fma_f32 v[224:225], v[18:19], v[186:187], v[190:191]
	v_pk_fma_f32 v[226:227], v[20:21], v[188:189], v[192:193]
	v_pk_fma_f32 v[228:229], v[2:3], v[202:203], v[206:207]
	v_pk_fma_f32 v[230:231], v[4:5], v[204:205], v[208:209]
	v_fmac_f32_dpp v224, v18, v182 row_shr:1 row_mask:0xf bank_mask:0xf bound_ctrl:1
	v_fmac_f32_dpp v225, v19, v183 row_shr:1 row_mask:0xf bank_mask:0xf bound_ctrl:1
	v_fmac_f32_dpp v226, v20, v184 row_shr:1 row_mask:0xf bank_mask:0xf bound_ctrl:1
	v_fmac_f32_dpp v227, v21, v185 row_shr:1 row_mask:0xf bank_mask:0xf bound_ctrl:1
	v_fmac_f32_dpp v228, v2, v198 row_shr:1 row_mask:0xf bank_mask:0xf bound_ctrl:1
	v_fmac_f32_dpp v229, v3, v199 row_shr:1 row_mask:0xf bank_mask:0xf bound_ctrl:1
	v_fmac_f32_dpp v230, v4, v200 row_shr:1 row_mask:0xf bank_mask:0xf bound_ctrl:1
	v_fmac_f32_dpp v231, v5, v201 row_shr:1 row_mask:0xf bank_mask:0xf bound_ctrl:1
	v_fmac_f32_dpp v224, v18, v178 row_shr:2 row_mask:0xf bank_mask:0xf bound_ctrl:1
	v_fmac_f32_dpp v225, v19, v179 row_shr:2 row_mask:0xf bank_mask:0xf bound_ctrl:1
	v_fmac_f32_dpp v226, v20, v180 row_shr:2 row_mask:0xf bank_mask:0xf bound_ctrl:1
	v_fmac_f32_dpp v227, v21, v181 row_shr:2 row_mask:0xf bank_mask:0xf bound_ctrl:1
	v_fmac_f32_dpp v228, v2, v194 row_shr:2 row_mask:0xf bank_mask:0xf bound_ctrl:1
	v_fmac_f32_dpp v229, v3, v195 row_shr:2 row_mask:0xf bank_mask:0xf bound_ctrl:1
	v_fmac_f32_dpp v230, v4, v196 row_shr:2 row_mask:0xf bank_mask:0xf bound_ctrl:1
	v_fmac_f32_dpp v231, v5, v197 row_shr:2 row_mask:0xf bank_mask:0xf bound_ctrl:1
	v_fmac_f32_dpp v224, v34, v182 row_shl:15 row_mask:0xf bank_mask:0xf bound_ctrl:1
	v_fmac_f32_dpp v225, v35, v183 row_shl:15 row_mask:0xf bank_mask:0xf bound_ctrl:1
	v_fmac_f32_dpp v226, v36, v184 row_shl:15 row_mask:0xf bank_mask:0xf bound_ctrl:1
	v_fmac_f32_dpp v227, v37, v185 row_shl:15 row_mask:0xf bank_mask:0xf bound_ctrl:1
	v_fmac_f32_dpp v228, v10, v198 row_shl:15 row_mask:0xf bank_mask:0xf bound_ctrl:1
	v_fmac_f32_dpp v229, v11, v199 row_shl:15 row_mask:0xf bank_mask:0xf bound_ctrl:1
	v_fmac_f32_dpp v230, v12, v200 row_shl:15 row_mask:0xf bank_mask:0xf bound_ctrl:1
	v_fmac_f32_dpp v231, v13, v201 row_shl:15 row_mask:0xf bank_mask:0xf bound_ctrl:1
	v_fmac_f32_dpp v224, v34, v178 row_shl:14 row_mask:0xf bank_mask:0xf bound_ctrl:1
	v_fmac_f32_dpp v225, v35, v179 row_shl:14 row_mask:0xf bank_mask:0xf bound_ctrl:1
	v_fmac_f32_dpp v226, v36, v180 row_shl:14 row_mask:0xf bank_mask:0xf bound_ctrl:1
	v_fmac_f32_dpp v227, v37, v181 row_shl:14 row_mask:0xf bank_mask:0xf bound_ctrl:1
	v_fmac_f32_dpp v228, v10, v194 row_shl:14 row_mask:0xf bank_mask:0xf bound_ctrl:1
	v_fmac_f32_dpp v229, v11, v195 row_shl:14 row_mask:0xf bank_mask:0xf bound_ctrl:1
	v_fmac_f32_dpp v230, v12, v196 row_shl:14 row_mask:0xf bank_mask:0xf bound_ctrl:1
	v_fmac_f32_dpp v231, v13, v197 row_shl:14 row_mask:0xf bank_mask:0xf bound_ctrl:1
	v_pk_mul_f32 v[232:233], v[224:225], s[48:49] op_sel_hi:[1,0]
	v_pk_mul_f32 v[234:235], v[226:227], s[48:49] op_sel_hi:[1,0]
	v_exp_f32_e32 v232, v232
	v_exp_f32_e32 v233, v233
	v_exp_f32_e32 v234, v234
	v_exp_f32_e32 v235, v235
	s_nop 0
	v_pk_add_f32 v[232:233], v[232:233], 1.0 op_sel_hi:[1,0]
	v_pk_add_f32 v[234:235], v[234:235], 1.0 op_sel_hi:[1,0]
	v_rcp_f32_e32 v232, v232
	v_rcp_f32_e32 v233, v233
	v_rcp_f32_e32 v234, v234
	v_rcp_f32_e32 v235, v235
	v_lshl_add_u64 v[220:221], v[220:221], 0, s[96:97]
	v_pk_mul_f32 v[224:225], v[224:225], v[232:233]
	v_pk_mul_f32 v[226:227], v[226:227], v[234:235]
	v_pk_mul_f32 v[224:225], v[224:225], v[228:229]
	v_pk_mul_f32 v[226:227], v[226:227], v[230:231]
	s_nop 0
	v_cvt_pk_bf16_f32 v168, v224, v225
	v_cvt_pk_bf16_f32 v169, v226, v227
	global_store_dwordx2 v[220:221], v[168:169], off offset:32
	s_branch .LBB0_1094
